# GEMM load segments: A-fragment LDS read bases kept in per-tile registers (no per-iteration adds), vmcnt and lgkmcnt waits merged into one instruction
# speedup vs baseline: 1.0021x; 1.0021x over previous
.LBB0_31:
	s_add_u32 s40, s12, 0x100
	v_mov_b32_e32 v0, 0
	s_addc_u32 s41, s13, 0
	s_mov_b32 s42, -2
	v_mov_b32_e32 v1, v0
	v_mov_b32_e32 v2, v0
	v_mov_b32_e32 v3, v0
	v_mov_b32_e32 v26, v0
	v_mov_b32_e32 v27, v0
	v_mov_b32_e32 v28, v0
	v_mov_b32_e32 v29, v0
	v_mov_b32_e32 v4, v0
	v_mov_b32_e32 v5, v0
	v_mov_b32_e32 v6, v0
	v_mov_b32_e32 v7, v0
	v_mov_b32_e32 v34, v0
	v_mov_b32_e32 v35, v0
	v_mov_b32_e32 v36, v0
	v_mov_b32_e32 v37, v0
	v_mov_b32_e32 v8, v0
	v_mov_b32_e32 v9, v0
	v_mov_b32_e32 v10, v0
	v_mov_b32_e32 v11, v0
	v_mov_b32_e32 v38, v0
	v_mov_b32_e32 v39, v0
	v_mov_b32_e32 v40, v0
	v_mov_b32_e32 v41, v0
	v_mov_b32_e32 v12, v0
	v_mov_b32_e32 v13, v0
	v_mov_b32_e32 v14, v0
	v_mov_b32_e32 v15, v0
	v_mov_b32_e32 v46, v0
	v_mov_b32_e32 v47, v0
	v_mov_b32_e32 v48, v0
	v_mov_b32_e32 v49, v0
	v_mov_b32_e32 v62, v0
	v_mov_b32_e32 v63, v0
	v_mov_b32_e32 v64, v0
	v_mov_b32_e32 v65, v0
	v_mov_b32_e32 v98, v0
	v_mov_b32_e32 v99, v0
	v_mov_b32_e32 v100, v0
	v_mov_b32_e32 v101, v0
	s_waitcnt vmcnt(0)
	v_mov_b32_e32 v70, v0
	v_mov_b32_e32 v71, v0
	v_mov_b32_e32 v72, v0
	v_mov_b32_e32 v73, v0
	v_mov_b32_e32 v102, v0
	v_mov_b32_e32 v103, v0
	v_mov_b32_e32 v104, v0
	v_mov_b32_e32 v105, v0
	v_mov_b32_e32 v74, v0
	v_mov_b32_e32 v75, v0
	v_mov_b32_e32 v76, v0
	v_mov_b32_e32 v77, v0
	v_mov_b32_e32 v106, v0
	v_mov_b32_e32 v107, v0
	v_mov_b32_e32 v108, v0
	v_mov_b32_e32 v109, v0
	v_mov_b32_e32 v78, v0
	v_mov_b32_e32 v79, v0
	v_mov_b32_e32 v80, v0
	v_mov_b32_e32 v81, v0
	v_mov_b32_e32 v110, v0
	v_mov_b32_e32 v111, v0
	v_mov_b32_e32 v112, v0
	v_mov_b32_e32 v113, v0
	v_mov_b32_e32 v18, v0
	v_mov_b32_e32 v19, v0
	v_mov_b32_e32 v20, v0
	v_mov_b32_e32 v21, v0
	v_mov_b32_e32 v50, v0
	v_mov_b32_e32 v51, v0
	v_mov_b32_e32 v52, v0
	v_mov_b32_e32 v53, v0
	v_mov_b32_e32 v22, v0
	v_mov_b32_e32 v23, v0
	v_mov_b32_e32 v24, v0
	v_mov_b32_e32 v25, v0
	v_mov_b32_e32 v54, v0
	v_mov_b32_e32 v55, v0
	v_mov_b32_e32 v56, v0
	v_mov_b32_e32 v57, v0
	v_mov_b32_e32 v30, v0
	v_mov_b32_e32 v31, v0
	v_mov_b32_e32 v32, v0
	v_mov_b32_e32 v33, v0
	v_mov_b32_e32 v58, v0
	v_mov_b32_e32 v59, v0
	v_mov_b32_e32 v60, v0
	v_mov_b32_e32 v61, v0
	v_mov_b32_e32 v42, v0
	v_mov_b32_e32 v43, v0
	v_mov_b32_e32 v44, v0
	v_mov_b32_e32 v45, v0
	v_mov_b32_e32 v66, v0
	v_mov_b32_e32 v67, v0
	v_mov_b32_e32 v68, v0
	v_mov_b32_e32 v69, v0
	v_mov_b32_e32 v82, v0
	v_mov_b32_e32 v83, v0
	v_mov_b32_e32 v84, v0
	v_mov_b32_e32 v85, v0
	v_mov_b32_e32 v114, v0
	v_mov_b32_e32 v115, v0
	v_mov_b32_e32 v116, v0
	v_mov_b32_e32 v117, v0
	v_mov_b32_e32 v86, v0
	v_mov_b32_e32 v87, v0
	v_mov_b32_e32 v88, v0
	v_mov_b32_e32 v89, v0
	v_mov_b32_e32 v118, v0
	v_mov_b32_e32 v119, v0
	v_mov_b32_e32 v120, v0
	v_mov_b32_e32 v121, v0
	v_mov_b32_e32 v90, v0
	v_mov_b32_e32 v91, v0
	v_mov_b32_e32 v92, v0
	v_mov_b32_e32 v93, v0
	v_mov_b32_e32 v122, v0
	v_mov_b32_e32 v123, v0
	v_mov_b32_e32 v124, v0
	v_mov_b32_e32 v125, v0
	v_mov_b32_e32 v94, v0
	v_mov_b32_e32 v95, v0
	v_mov_b32_e32 v96, v0
	v_mov_b32_e32 v97, v0
	v_mov_b32_e32 v126, v0
	v_mov_b32_e32 v127, v0
	v_mov_b32_e32 v128, v0
	v_mov_b32_e32 v129, v0
	v_add_u32_e32 v204, 0x10000, v207
	v_add_u32_e32 v205, 0x14000, v207
	v_add_u32_e32 v210, 0x18000, v207
	v_add_u32_e32 v211, 0x1c000, v207
.LBB0_32:
	s_add_u32 s12, s10, 0x100
	s_addc_u32 s13, s11, 0
	s_cmpk_eq_i32 s42, 0x52
	s_cselect_b32 s17, s1, s13
	s_cselect_b32 s16, s0, s12
	s_cselect_b32 s15, s9, s41
	s_cselect_b32 s14, s8, s40
	ds_read_b128 v[130:133], v204
	ds_read_b128 v[134:137], v204 offset:1024
	ds_read_b128 v[138:141], v204 offset:2048
	ds_read_b128 v[142:145], v204 offset:3072
	ds_read_b128 v[146:149], v205
	ds_read_b128 v[150:153], v205 offset:1024
	ds_read_b128 v[154:157], v205 offset:2048
	ds_read_b128 v[158:161], v205 offset:3072
	ds_read_b128 v[162:165], v208
	ds_read_b128 v[166:169], v208 offset:1024
	ds_read_b128 v[170:173], v208 offset:2048
	ds_read_b128 v[184:187], v208 offset:3072
	ds_read_b128 v[188:191], v208 offset:4096
	s_add_i32 m0, s23, 0xc000
	ds_read_b128 v[192:195], v208 offset:5120
	global_load_lds_dwordx4 v180, s[10:11]
	s_add_i32 m0, s23, 0xe000
	ds_read_b128 v[196:199], v208 offset:6144
	global_load_lds_dwordx4 v182, s[10:11]
	ds_read_b128 v[200:203], v208 offset:7168
	s_waitcnt vmcnt(8) lgkmcnt(0)
	s_barrier
	v_mfma_f32_16x16x32_bf16 v[126:129], v[130:133], v[162:165], v[126:129]
	v_mfma_f32_16x16x32_bf16 v[94:97], v[138:141], v[162:165], v[94:97]
	v_mfma_f32_16x16x32_bf16 v[122:125], v[130:133], v[170:173], v[122:125]
	v_mfma_f32_16x16x32_bf16 v[90:93], v[138:141], v[170:173], v[90:93]
	v_mfma_f32_16x16x32_bf16 v[118:121], v[130:133], v[188:191], v[118:121]
	v_mfma_f32_16x16x32_bf16 v[86:89], v[138:141], v[188:191], v[86:89]
	v_mfma_f32_16x16x32_bf16 v[114:117], v[130:133], v[196:199], v[114:117]
	v_mfma_f32_16x16x32_bf16 v[82:85], v[138:141], v[196:199], v[82:85]
	v_mfma_f32_16x16x32_bf16 v[126:129], v[134:137], v[166:169], v[126:129]
	v_mfma_f32_16x16x32_bf16 v[94:97], v[142:145], v[166:169], v[94:97]
	v_mfma_f32_16x16x32_bf16 v[122:125], v[134:137], v[184:187], v[122:125]
	v_mfma_f32_16x16x32_bf16 v[90:93], v[142:145], v[184:187], v[90:93]
	v_mfma_f32_16x16x32_bf16 v[118:121], v[134:137], v[192:195], v[118:121]
	v_mfma_f32_16x16x32_bf16 v[86:89], v[142:145], v[192:195], v[86:89]
	v_mfma_f32_16x16x32_bf16 v[114:117], v[134:137], v[200:203], v[114:117]
	v_mfma_f32_16x16x32_bf16 v[82:85], v[142:145], v[200:203], v[82:85]
	v_mfma_f32_16x16x32_bf16 v[66:69], v[146:149], v[162:165], v[66:69]
	v_mfma_f32_16x16x32_bf16 v[42:45], v[154:157], v[162:165], v[42:45]
	v_mfma_f32_16x16x32_bf16 v[58:61], v[146:149], v[170:173], v[58:61]
	v_mfma_f32_16x16x32_bf16 v[30:33], v[154:157], v[170:173], v[30:33]
	v_mfma_f32_16x16x32_bf16 v[54:57], v[146:149], v[188:191], v[54:57]
	v_mfma_f32_16x16x32_bf16 v[22:25], v[154:157], v[188:191], v[22:25]
	v_mfma_f32_16x16x32_bf16 v[50:53], v[146:149], v[196:199], v[50:53]
	v_mfma_f32_16x16x32_bf16 v[18:21], v[154:157], v[196:199], v[18:21]
	v_mfma_f32_16x16x32_bf16 v[66:69], v[150:153], v[166:169], v[66:69]
	v_mfma_f32_16x16x32_bf16 v[42:45], v[158:161], v[166:169], v[42:45]
	v_mfma_f32_16x16x32_bf16 v[58:61], v[150:153], v[184:187], v[58:61]
	v_mfma_f32_16x16x32_bf16 v[30:33], v[158:161], v[184:187], v[30:33]
	v_mfma_f32_16x16x32_bf16 v[54:57], v[150:153], v[192:195], v[54:57]
	v_mfma_f32_16x16x32_bf16 v[22:25], v[158:161], v[192:195], v[22:25]
	v_mfma_f32_16x16x32_bf16 v[50:53], v[150:153], v[200:203], v[50:53]
	v_mfma_f32_16x16x32_bf16 v[18:21], v[158:161], v[200:203], v[18:21]
	s_barrier
	ds_read_b128 v[162:165], v208 offset:16384
	s_add_i32 m0, s22, 0x10000
	ds_read_b128 v[166:169], v208 offset:17408
	global_load_lds_dwordx4 v178, s[14:15]
	s_add_i32 m0, s22, 0x12000
	s_add_u32 s10, s14, 0x158000
	s_addc_u32 s11, s15, 0
	ds_read_b128 v[170:173], v208 offset:18432
	global_load_lds_dwordx4 v176, s[14:15]
	s_add_i32 m0, s22, 0x14000
	ds_read_b128 v[184:187], v208 offset:19456
	global_load_lds_dwordx4 v178, s[10:11]
	s_add_i32 m0, s22, 0x16000
	ds_read_b128 v[188:191], v208 offset:20480
	global_load_lds_dwordx4 v176, s[10:11]
	s_mov_b32 m0, s23
	ds_read_b128 v[192:195], v208 offset:21504
	global_load_lds_dwordx4 v178, s[16:17]
	s_mov_b32 m0, s24
	ds_read_b128 v[196:199], v208 offset:22528
	global_load_lds_dwordx4 v176, s[16:17]
	ds_read_b128 v[200:203], v208 offset:23552
	s_waitcnt vmcnt(8) lgkmcnt(0)
	s_barrier
	v_mfma_f32_16x16x32_bf16 v[110:113], v[130:133], v[162:165], v[110:113]
	v_mfma_f32_16x16x32_bf16 v[78:81], v[138:141], v[162:165], v[78:81]
	v_mfma_f32_16x16x32_bf16 v[106:109], v[130:133], v[170:173], v[106:109]
	v_mfma_f32_16x16x32_bf16 v[74:77], v[138:141], v[170:173], v[74:77]
	v_mfma_f32_16x16x32_bf16 v[102:105], v[130:133], v[188:191], v[102:105]
	v_mfma_f32_16x16x32_bf16 v[70:73], v[138:141], v[188:191], v[70:73]
	v_mfma_f32_16x16x32_bf16 v[98:101], v[130:133], v[196:199], v[98:101]
	v_mfma_f32_16x16x32_bf16 v[62:65], v[138:141], v[196:199], v[62:65]
	v_mfma_f32_16x16x32_bf16 v[110:113], v[134:137], v[166:169], v[110:113]
	v_mfma_f32_16x16x32_bf16 v[78:81], v[142:145], v[166:169], v[78:81]
	v_mfma_f32_16x16x32_bf16 v[106:109], v[134:137], v[184:187], v[106:109]
	v_mfma_f32_16x16x32_bf16 v[74:77], v[142:145], v[184:187], v[74:77]
	v_mfma_f32_16x16x32_bf16 v[102:105], v[134:137], v[192:195], v[102:105]
	v_mfma_f32_16x16x32_bf16 v[70:73], v[142:145], v[192:195], v[70:73]
	v_mfma_f32_16x16x32_bf16 v[98:101], v[134:137], v[200:203], v[98:101]
	v_mfma_f32_16x16x32_bf16 v[62:65], v[142:145], v[200:203], v[62:65]
	v_mfma_f32_16x16x32_bf16 v[46:49], v[146:149], v[162:165], v[46:49]
	v_mfma_f32_16x16x32_bf16 v[12:15], v[154:157], v[162:165], v[12:15]
	v_mfma_f32_16x16x32_bf16 v[38:41], v[146:149], v[170:173], v[38:41]
	v_mfma_f32_16x16x32_bf16 v[8:11], v[154:157], v[170:173], v[8:11]
	v_mfma_f32_16x16x32_bf16 v[34:37], v[146:149], v[188:191], v[34:37]
	v_mfma_f32_16x16x32_bf16 v[4:7], v[154:157], v[188:191], v[4:7]
	v_mfma_f32_16x16x32_bf16 v[26:29], v[146:149], v[196:199], v[26:29]
	v_mfma_f32_16x16x32_bf16 v[0:3], v[154:157], v[196:199], v[0:3]
	v_mfma_f32_16x16x32_bf16 v[46:49], v[150:153], v[166:169], v[46:49]
	v_mfma_f32_16x16x32_bf16 v[12:15], v[158:161], v[166:169], v[12:15]
	v_mfma_f32_16x16x32_bf16 v[38:41], v[150:153], v[184:187], v[38:41]
	v_mfma_f32_16x16x32_bf16 v[8:11], v[158:161], v[184:187], v[8:11]
	v_mfma_f32_16x16x32_bf16 v[34:37], v[150:153], v[192:195], v[34:37]
	v_mfma_f32_16x16x32_bf16 v[4:7], v[158:161], v[192:195], v[4:7]
	v_mfma_f32_16x16x32_bf16 v[26:29], v[150:153], v[200:203], v[26:29]
	v_mfma_f32_16x16x32_bf16 v[0:3], v[158:161], v[200:203], v[0:3]
	s_barrier
	s_add_u32 s100, s16, 0x158000
	s_addc_u32 s101, s17, 0
	ds_read_b128 v[130:133], v210
	ds_read_b128 v[134:137], v210 offset:1024
	ds_read_b128 v[138:141], v210 offset:2048
	ds_read_b128 v[142:145], v210 offset:3072
	ds_read_b128 v[146:149], v211
	ds_read_b128 v[150:153], v211 offset:1024
	ds_read_b128 v[154:157], v211 offset:2048
	ds_read_b128 v[158:161], v211 offset:3072
	ds_read_b128 v[162:165], v208 offset:32768
	ds_read_b128 v[166:169], v208 offset:33792
	ds_read_b128 v[170:173], v208 offset:34816
	ds_read_b128 v[184:187], v208 offset:35840
	ds_read_b128 v[188:191], v208 offset:36864
	s_mov_b32 m0, s25
	ds_read_b128 v[192:195], v208 offset:37888
	global_load_lds_dwordx4 v178, s[100:101]
	s_mov_b32 m0, s26
	ds_read_b128 v[196:199], v208 offset:38912
	global_load_lds_dwordx4 v176, s[100:101]
	ds_read_b128 v[200:203], v208 offset:39936
	s_waitcnt vmcnt(8) lgkmcnt(0)
	s_barrier
	v_mfma_f32_16x16x32_bf16 v[126:129], v[130:133], v[162:165], v[126:129]
	v_mfma_f32_16x16x32_bf16 v[94:97], v[138:141], v[162:165], v[94:97]
	v_mfma_f32_16x16x32_bf16 v[122:125], v[130:133], v[170:173], v[122:125]
	v_mfma_f32_16x16x32_bf16 v[90:93], v[138:141], v[170:173], v[90:93]
	v_mfma_f32_16x16x32_bf16 v[118:121], v[130:133], v[188:191], v[118:121]
	v_mfma_f32_16x16x32_bf16 v[86:89], v[138:141], v[188:191], v[86:89]
	v_mfma_f32_16x16x32_bf16 v[114:117], v[130:133], v[196:199], v[114:117]
	v_mfma_f32_16x16x32_bf16 v[82:85], v[138:141], v[196:199], v[82:85]
	v_mfma_f32_16x16x32_bf16 v[126:129], v[134:137], v[166:169], v[126:129]
	v_mfma_f32_16x16x32_bf16 v[94:97], v[142:145], v[166:169], v[94:97]
	v_mfma_f32_16x16x32_bf16 v[122:125], v[134:137], v[184:187], v[122:125]
	v_mfma_f32_16x16x32_bf16 v[90:93], v[142:145], v[184:187], v[90:93]
	v_mfma_f32_16x16x32_bf16 v[118:121], v[134:137], v[192:195], v[118:121]
	v_mfma_f32_16x16x32_bf16 v[86:89], v[142:145], v[192:195], v[86:89]
	v_mfma_f32_16x16x32_bf16 v[114:117], v[134:137], v[200:203], v[114:117]
	v_mfma_f32_16x16x32_bf16 v[82:85], v[142:145], v[200:203], v[82:85]
	v_mfma_f32_16x16x32_bf16 v[66:69], v[146:149], v[162:165], v[66:69]
	v_mfma_f32_16x16x32_bf16 v[42:45], v[154:157], v[162:165], v[42:45]
	v_mfma_f32_16x16x32_bf16 v[58:61], v[146:149], v[170:173], v[58:61]
	v_mfma_f32_16x16x32_bf16 v[30:33], v[154:157], v[170:173], v[30:33]
	v_mfma_f32_16x16x32_bf16 v[54:57], v[146:149], v[188:191], v[54:57]
	v_mfma_f32_16x16x32_bf16 v[22:25], v[154:157], v[188:191], v[22:25]
	v_mfma_f32_16x16x32_bf16 v[50:53], v[146:149], v[196:199], v[50:53]
	v_mfma_f32_16x16x32_bf16 v[18:21], v[154:157], v[196:199], v[18:21]
	v_mfma_f32_16x16x32_bf16 v[66:69], v[150:153], v[166:169], v[66:69]
	v_mfma_f32_16x16x32_bf16 v[42:45], v[158:161], v[166:169], v[42:45]
	v_mfma_f32_16x16x32_bf16 v[58:61], v[150:153], v[184:187], v[58:61]
	v_mfma_f32_16x16x32_bf16 v[30:33], v[158:161], v[184:187], v[30:33]
	v_mfma_f32_16x16x32_bf16 v[54:57], v[150:153], v[192:195], v[54:57]
	v_mfma_f32_16x16x32_bf16 v[22:25], v[158:161], v[192:195], v[22:25]
	v_mfma_f32_16x16x32_bf16 v[50:53], v[150:153], v[200:203], v[50:53]
	v_mfma_f32_16x16x32_bf16 v[18:21], v[158:161], v[200:203], v[18:21]
	s_barrier
	ds_read_b128 v[162:165], v208 offset:49152
	s_add_i32 m0, s22, 0x17f80
	ds_read_b128 v[166:169], v208 offset:50176
	global_load_lds_dwordx4 v178, s[14:15] offset:128
	s_add_i32 m0, s22, 0x19f80
	ds_read_b128 v[170:173], v208 offset:51200
	global_load_lds_dwordx4 v176, s[14:15] offset:128
	s_add_i32 m0, s22, 0x1bf80
	ds_read_b128 v[184:187], v208 offset:52224
	global_load_lds_dwordx4 v178, s[10:11] offset:128
	s_add_i32 m0, s22, 0x1df80
	ds_read_b128 v[188:191], v208 offset:53248
	global_load_lds_dwordx4 v176, s[10:11] offset:128
	s_add_i32 m0, s31, 0xffffff80
	ds_read_b128 v[192:195], v208 offset:54272
	global_load_lds_dwordx4 v178, s[16:17] offset:128
	s_add_i32 m0, s34, 0xffffff80
	ds_read_b128 v[196:199], v208 offset:55296
	global_load_lds_dwordx4 v176, s[16:17] offset:128
	ds_read_b128 v[200:203], v208 offset:56320
	s_waitcnt vmcnt(8) lgkmcnt(0)
	s_barrier
	v_mfma_f32_16x16x32_bf16 v[110:113], v[130:133], v[162:165], v[110:113]
	v_mfma_f32_16x16x32_bf16 v[78:81], v[138:141], v[162:165], v[78:81]
	v_mfma_f32_16x16x32_bf16 v[106:109], v[130:133], v[170:173], v[106:109]
	v_mfma_f32_16x16x32_bf16 v[74:77], v[138:141], v[170:173], v[74:77]
	v_mfma_f32_16x16x32_bf16 v[102:105], v[130:133], v[188:191], v[102:105]
	v_mfma_f32_16x16x32_bf16 v[70:73], v[138:141], v[188:191], v[70:73]
	v_mfma_f32_16x16x32_bf16 v[98:101], v[130:133], v[196:199], v[98:101]
	v_mfma_f32_16x16x32_bf16 v[62:65], v[138:141], v[196:199], v[62:65]
	v_mfma_f32_16x16x32_bf16 v[110:113], v[134:137], v[166:169], v[110:113]
	v_mfma_f32_16x16x32_bf16 v[78:81], v[142:145], v[166:169], v[78:81]
	v_mfma_f32_16x16x32_bf16 v[106:109], v[134:137], v[184:187], v[106:109]
	v_mfma_f32_16x16x32_bf16 v[74:77], v[142:145], v[184:187], v[74:77]
	v_mfma_f32_16x16x32_bf16 v[102:105], v[134:137], v[192:195], v[102:105]
	v_mfma_f32_16x16x32_bf16 v[70:73], v[142:145], v[192:195], v[70:73]
	v_mfma_f32_16x16x32_bf16 v[98:101], v[134:137], v[200:203], v[98:101]
	v_mfma_f32_16x16x32_bf16 v[62:65], v[142:145], v[200:203], v[62:65]
	v_mfma_f32_16x16x32_bf16 v[46:49], v[146:149], v[162:165], v[46:49]
	v_mfma_f32_16x16x32_bf16 v[12:15], v[154:157], v[162:165], v[12:15]
	v_mfma_f32_16x16x32_bf16 v[38:41], v[146:149], v[170:173], v[38:41]
	v_mfma_f32_16x16x32_bf16 v[8:11], v[154:157], v[170:173], v[8:11]
	v_mfma_f32_16x16x32_bf16 v[34:37], v[146:149], v[188:191], v[34:37]
	v_mfma_f32_16x16x32_bf16 v[4:7], v[154:157], v[188:191], v[4:7]
	v_mfma_f32_16x16x32_bf16 v[26:29], v[146:149], v[196:199], v[26:29]
	v_mfma_f32_16x16x32_bf16 v[0:3], v[154:157], v[196:199], v[0:3]
	v_mfma_f32_16x16x32_bf16 v[46:49], v[150:153], v[166:169], v[46:49]
	v_mfma_f32_16x16x32_bf16 v[12:15], v[158:161], v[166:169], v[12:15]
	v_mfma_f32_16x16x32_bf16 v[38:41], v[150:153], v[184:187], v[38:41]
	v_mfma_f32_16x16x32_bf16 v[8:11], v[158:161], v[184:187], v[8:11]
	v_mfma_f32_16x16x32_bf16 v[34:37], v[150:153], v[192:195], v[34:37]
	v_mfma_f32_16x16x32_bf16 v[4:7], v[158:161], v[192:195], v[4:7]
	v_mfma_f32_16x16x32_bf16 v[26:29], v[150:153], v[200:203], v[26:29]
	v_mfma_f32_16x16x32_bf16 v[0:3], v[158:161], v[200:203], v[0:3]
	s_barrier
	s_add_i32 s42, s42, 2
	s_add_u32 s40, s40, 0x100
	s_addc_u32 s41, s41, 0
	s_cmpk_gt_u32 s42, 0x53
	s_mov_b64 s[10:11], s[12:13]
	s_cbranch_scc0 .LBB0_32
	s_and_b64 vcc, exec, s[6:7]
	s_cbranch_vccz .LBB0_35
	s_barrier

.LBB0_67:
	s_ashr_i32 s21, s20, 31
	s_lshl_b64 s[10:11], s[20:21], 20
	s_add_u32 s22, s34, s10
	s_addc_u32 s23, s35, s11
	s_and_b64 s[10:11], s[4:5], exec
	s_cselect_b32 s21, s23, s7
	s_cselect_b32 s28, s22, s6
	s_ashr_i32 s19, s18, 31
	s_lshl_b64 s[10:11], s[18:19], 20
	s_add_u32 s24, s36, s10
	s_addc_u32 s25, s37, s11
	s_and_b64 s[10:11], s[4:5], exec
	s_cselect_b32 s19, s25, s9
	s_cselect_b32 s29, s24, s8
	s_add_u32 s6, s6, 0x80080
	s_addc_u32 s7, s7, 0
	s_add_u32 s30, s8, 0x100
	v_mov_b32_e32 v4, 0
	s_addc_u32 s31, s9, 0
	s_mov_b32 s51, -2
	v_mov_b32_e32 v5, v4
	v_mov_b32_e32 v6, v4
	v_mov_b32_e32 v7, v4
	v_mov_b32_e32 v0, v4
	v_mov_b32_e32 v1, v4
	v_mov_b32_e32 v2, v4
	v_mov_b32_e32 v3, v4
	v_mov_b32_e32 v26, v4
	v_mov_b32_e32 v27, v4
	v_mov_b32_e32 v28, v4
	v_mov_b32_e32 v29, v4
	v_mov_b32_e32 v34, v4
	v_mov_b32_e32 v35, v4
	v_mov_b32_e32 v36, v4
	v_mov_b32_e32 v37, v4
	v_mov_b32_e32 v42, v4
	v_mov_b32_e32 v43, v4
	v_mov_b32_e32 v44, v4
	v_mov_b32_e32 v45, v4
	v_mov_b32_e32 v50, v4
	v_mov_b32_e32 v51, v4
	v_mov_b32_e32 v52, v4
	v_mov_b32_e32 v53, v4
	v_mov_b32_e32 v90, v4
	v_mov_b32_e32 v91, v4
	v_mov_b32_e32 v92, v4
	v_mov_b32_e32 v93, v4
	v_mov_b32_e32 v94, v4
	v_mov_b32_e32 v95, v4
	v_mov_b32_e32 v96, v4
	v_mov_b32_e32 v97, v4
	v_mov_b32_e32 v12, v4
	v_mov_b32_e32 v13, v4
	v_mov_b32_e32 v14, v4
	v_mov_b32_e32 v15, v4
	v_mov_b32_e32 v8, v4
	v_mov_b32_e32 v9, v4
	v_mov_b32_e32 v10, v4
	v_mov_b32_e32 v11, v4
	v_mov_b32_e32 v18, v4
	v_mov_b32_e32 v19, v4
	v_mov_b32_e32 v20, v4
	v_mov_b32_e32 v21, v4
	v_mov_b32_e32 v22, v4
	v_mov_b32_e32 v23, v4
	v_mov_b32_e32 v24, v4
	v_mov_b32_e32 v25, v4
	v_mov_b32_e32 v30, v4
	v_mov_b32_e32 v31, v4
	v_mov_b32_e32 v32, v4
	v_mov_b32_e32 v33, v4
	v_mov_b32_e32 v38, v4
	v_mov_b32_e32 v39, v4
	v_mov_b32_e32 v40, v4
	v_mov_b32_e32 v41, v4
	v_mov_b32_e32 v46, v4
	v_mov_b32_e32 v47, v4
	v_mov_b32_e32 v48, v4
	v_mov_b32_e32 v49, v4
	s_waitcnt vmcnt(0)
	v_mov_b32_e32 v58, v4
	v_mov_b32_e32 v59, v4
	v_mov_b32_e32 v60, v4
	v_mov_b32_e32 v61, v4
	v_mov_b32_e32 v98, v4
	v_mov_b32_e32 v99, v4
	v_mov_b32_e32 v100, v4
	v_mov_b32_e32 v101, v4
	v_mov_b32_e32 v102, v4
	v_mov_b32_e32 v103, v4
	v_mov_b32_e32 v104, v4
	v_mov_b32_e32 v105, v4
	v_mov_b32_e32 v122, v4
	v_mov_b32_e32 v123, v4
	v_mov_b32_e32 v124, v4
	v_mov_b32_e32 v125, v4
	v_mov_b32_e32 v130, v4
	v_mov_b32_e32 v131, v4
	v_mov_b32_e32 v132, v4
	v_mov_b32_e32 v133, v4
	v_mov_b32_e32 v138, v4
	v_mov_b32_e32 v139, v4
	v_mov_b32_e32 v140, v4
	v_mov_b32_e32 v141, v4
	v_mov_b32_e32 v146, v4
	v_mov_b32_e32 v147, v4
	v_mov_b32_e32 v148, v4
	v_mov_b32_e32 v149, v4
	v_mov_b32_e32 v154, v4
	v_mov_b32_e32 v155, v4
	v_mov_b32_e32 v156, v4
	v_mov_b32_e32 v157, v4
	v_mov_b32_e32 v158, v4
	v_mov_b32_e32 v159, v4
	v_mov_b32_e32 v160, v4
	v_mov_b32_e32 v161, v4
	v_mov_b32_e32 v106, v4
	v_mov_b32_e32 v107, v4
	v_mov_b32_e32 v108, v4
	v_mov_b32_e32 v109, v4
	v_mov_b32_e32 v110, v4
	v_mov_b32_e32 v111, v4
	v_mov_b32_e32 v112, v4
	v_mov_b32_e32 v113, v4
	v_mov_b32_e32 v114, v4
	v_mov_b32_e32 v115, v4
	v_mov_b32_e32 v116, v4
	v_mov_b32_e32 v117, v4
	v_mov_b32_e32 v118, v4
	v_mov_b32_e32 v119, v4
	v_mov_b32_e32 v120, v4
	v_mov_b32_e32 v121, v4
	v_mov_b32_e32 v126, v4
	v_mov_b32_e32 v127, v4
	v_mov_b32_e32 v128, v4
	v_mov_b32_e32 v129, v4
	v_mov_b32_e32 v134, v4
	v_mov_b32_e32 v135, v4
	v_mov_b32_e32 v136, v4
	v_mov_b32_e32 v137, v4
	v_mov_b32_e32 v142, v4
	v_mov_b32_e32 v143, v4
	v_mov_b32_e32 v144, v4
	v_mov_b32_e32 v145, v4
	v_mov_b32_e32 v150, v4
	v_mov_b32_e32 v151, v4
	v_mov_b32_e32 v152, v4
	v_mov_b32_e32 v153, v4
	v_add_u32_e32 v214, 0x10000, v190
	v_add_u32_e32 v215, 0x14000, v190
	v_add_u32_e32 v234, 0x18000, v190
	v_add_u32_e32 v235, 0x1c000, v190
.LBB0_68:
	s_add_u32 s8, s6, 0xfff80080
	s_addc_u32 s9, s7, -1
	s_cmp_eq_u32 s51, 28
	s_cselect_b32 s11, s21, s9
	s_cselect_b32 s10, s28, s8
	s_cselect_b32 s9, s19, s31
	s_cselect_b32 s8, s29, s30
	ds_read_b128 v[54:57], v214
	ds_read_b128 v[62:65], v214 offset:1024
	ds_read_b128 v[66:69], v214 offset:2048
	ds_read_b128 v[70:73], v214 offset:3072
	ds_read_b128 v[74:77], v215
	ds_read_b128 v[78:81], v215 offset:1024
	ds_read_b128 v[82:85], v215 offset:2048
	ds_read_b128 v[86:89], v215 offset:3072
	ds_read_b128 v[170:173], v192
	ds_read_b128 v[184:187], v192 offset:1024
	ds_read_b128 v[194:197], v192 offset:2048
	ds_read_b128 v[198:201], v192 offset:3072
	ds_read_b128 v[202:205], v192 offset:4096
	s_add_i32 m0, s41, 0xc000
	ds_read_b128 v[206:209], v192 offset:5120
	global_load_lds_dwordx4 v180, s[6:7]
	s_add_i32 m0, s41, 0xe000
	ds_read_b128 v[210:213], v192 offset:6144
	global_load_lds_dwordx4 v182, s[6:7]
	ds_read_b128 v[222:225], v192 offset:7168
	s_waitcnt vmcnt(8) lgkmcnt(0)
	s_barrier
	v_mfma_f32_16x16x32_bf16 v[150:153], v[54:57], v[170:173], v[150:153]
	v_mfma_f32_16x16x32_bf16 v[142:145], v[66:69], v[170:173], v[142:145]
	v_mfma_f32_16x16x32_bf16 v[134:137], v[54:57], v[194:197], v[134:137]
	v_mfma_f32_16x16x32_bf16 v[126:129], v[66:69], v[194:197], v[126:129]
	v_mfma_f32_16x16x32_bf16 v[118:121], v[54:57], v[202:205], v[118:121]
	v_mfma_f32_16x16x32_bf16 v[114:117], v[66:69], v[202:205], v[114:117]
	v_mfma_f32_16x16x32_bf16 v[110:113], v[54:57], v[210:213], v[110:113]
	v_mfma_f32_16x16x32_bf16 v[106:109], v[66:69], v[210:213], v[106:109]
	v_mfma_f32_16x16x32_bf16 v[150:153], v[62:65], v[184:187], v[150:153]
	v_mfma_f32_16x16x32_bf16 v[142:145], v[70:73], v[184:187], v[142:145]
	v_mfma_f32_16x16x32_bf16 v[134:137], v[62:65], v[198:201], v[134:137]
	v_mfma_f32_16x16x32_bf16 v[126:129], v[70:73], v[198:201], v[126:129]
	v_mfma_f32_16x16x32_bf16 v[118:121], v[62:65], v[206:209], v[118:121]
	v_mfma_f32_16x16x32_bf16 v[114:117], v[70:73], v[206:209], v[114:117]
	v_mfma_f32_16x16x32_bf16 v[110:113], v[62:65], v[222:225], v[110:113]
	v_mfma_f32_16x16x32_bf16 v[106:109], v[70:73], v[222:225], v[106:109]
	v_mfma_f32_16x16x32_bf16 v[158:161], v[74:77], v[170:173], v[158:161]
	v_mfma_f32_16x16x32_bf16 v[154:157], v[82:85], v[170:173], v[154:157]
	v_mfma_f32_16x16x32_bf16 v[146:149], v[74:77], v[194:197], v[146:149]
	v_mfma_f32_16x16x32_bf16 v[138:141], v[82:85], v[194:197], v[138:141]
	v_mfma_f32_16x16x32_bf16 v[130:133], v[74:77], v[202:205], v[130:133]
	v_mfma_f32_16x16x32_bf16 v[122:125], v[82:85], v[202:205], v[122:125]
	v_mfma_f32_16x16x32_bf16 v[102:105], v[74:77], v[210:213], v[102:105]
	v_mfma_f32_16x16x32_bf16 v[98:101], v[82:85], v[210:213], v[98:101]
	v_mfma_f32_16x16x32_bf16 v[158:161], v[78:81], v[184:187], v[158:161]
	v_mfma_f32_16x16x32_bf16 v[154:157], v[86:89], v[184:187], v[154:157]
	v_mfma_f32_16x16x32_bf16 v[146:149], v[78:81], v[198:201], v[146:149]
	v_mfma_f32_16x16x32_bf16 v[138:141], v[86:89], v[198:201], v[138:141]
	v_mfma_f32_16x16x32_bf16 v[130:133], v[78:81], v[206:209], v[130:133]
	v_mfma_f32_16x16x32_bf16 v[122:125], v[86:89], v[206:209], v[122:125]
	v_mfma_f32_16x16x32_bf16 v[102:105], v[78:81], v[222:225], v[102:105]
	v_mfma_f32_16x16x32_bf16 v[98:101], v[86:89], v[222:225], v[98:101]
	s_barrier
	ds_read_b128 v[170:173], v192 offset:16384
	s_add_i32 m0, s38, 0x10000
	ds_read_b128 v[184:187], v192 offset:17408
	global_load_lds_dwordx4 v166, s[8:9]
	s_add_i32 m0, s38, 0x12000
	s_add_u32 s52, s8, 0x80000
	s_addc_u32 s53, s9, 0
	ds_read_b128 v[194:197], v192 offset:18432
	global_load_lds_dwordx4 v162, s[8:9]
	s_add_i32 m0, s38, 0x14000
	ds_read_b128 v[198:201], v192 offset:19456
	global_load_lds_dwordx4 v166, s[52:53]
	s_add_i32 m0, s38, 0x16000
	ds_read_b128 v[202:205], v192 offset:20480
	global_load_lds_dwordx4 v162, s[52:53]
	s_mov_b32 m0, s41
	ds_read_b128 v[206:209], v192 offset:21504
	global_load_lds_dwordx4 v168, s[10:11]
	s_mov_b32 m0, s42
	ds_read_b128 v[210:213], v192 offset:22528
	global_load_lds_dwordx4 v164, s[10:11]
	ds_read_b128 v[222:225], v192 offset:23552
	s_waitcnt vmcnt(8) lgkmcnt(0)
	s_barrier
	v_mfma_f32_16x16x32_bf16 v[58:61], v[54:57], v[170:173], v[58:61]
	v_mfma_f32_16x16x32_bf16 v[46:49], v[66:69], v[170:173], v[46:49]
	v_mfma_f32_16x16x32_bf16 v[38:41], v[54:57], v[194:197], v[38:41]
	v_mfma_f32_16x16x32_bf16 v[30:33], v[66:69], v[194:197], v[30:33]
	v_mfma_f32_16x16x32_bf16 v[22:25], v[54:57], v[202:205], v[22:25]
	v_mfma_f32_16x16x32_bf16 v[18:21], v[66:69], v[202:205], v[18:21]
	v_mfma_f32_16x16x32_bf16 v[8:11], v[54:57], v[210:213], v[8:11]
	v_mfma_f32_16x16x32_bf16 v[12:15], v[66:69], v[210:213], v[12:15]
	v_mfma_f32_16x16x32_bf16 v[58:61], v[62:65], v[184:187], v[58:61]
	v_mfma_f32_16x16x32_bf16 v[46:49], v[70:73], v[184:187], v[46:49]
	v_mfma_f32_16x16x32_bf16 v[38:41], v[62:65], v[198:201], v[38:41]
	v_mfma_f32_16x16x32_bf16 v[30:33], v[70:73], v[198:201], v[30:33]
	v_mfma_f32_16x16x32_bf16 v[22:25], v[62:65], v[206:209], v[22:25]
	v_mfma_f32_16x16x32_bf16 v[18:21], v[70:73], v[206:209], v[18:21]
	v_mfma_f32_16x16x32_bf16 v[8:11], v[62:65], v[222:225], v[8:11]
	v_mfma_f32_16x16x32_bf16 v[12:15], v[70:73], v[222:225], v[12:15]
	v_mfma_f32_16x16x32_bf16 v[50:53], v[74:77], v[194:197], v[50:53]
	v_mfma_f32_16x16x32_bf16 v[42:45], v[82:85], v[194:197], v[42:45]
	v_mfma_f32_16x16x32_bf16 v[34:37], v[74:77], v[202:205], v[34:37]
	v_mfma_f32_16x16x32_bf16 v[26:29], v[82:85], v[202:205], v[26:29]
	v_mfma_f32_16x16x32_bf16 v[0:3], v[74:77], v[210:213], v[0:3]
	v_mfma_f32_16x16x32_bf16 v[4:7], v[82:85], v[210:213], v[4:7]
	v_mfma_f32_16x16x32_bf16 v[54:57], v[74:77], v[170:173], v[94:97]
	v_mfma_f32_16x16x32_bf16 v[62:65], v[82:85], v[170:173], v[90:93]
	v_mfma_f32_16x16x32_bf16 v[50:53], v[78:81], v[198:201], v[50:53]
	v_mfma_f32_16x16x32_bf16 v[42:45], v[86:89], v[198:201], v[42:45]
	v_mfma_f32_16x16x32_bf16 v[34:37], v[78:81], v[206:209], v[34:37]
	v_mfma_f32_16x16x32_bf16 v[26:29], v[86:89], v[206:209], v[26:29]
	v_mfma_f32_16x16x32_bf16 v[0:3], v[78:81], v[222:225], v[0:3]
	v_mfma_f32_16x16x32_bf16 v[4:7], v[86:89], v[222:225], v[4:7]
	v_mfma_f32_16x16x32_bf16 v[54:57], v[78:81], v[184:187], v[54:57]
	v_mfma_f32_16x16x32_bf16 v[62:65], v[86:89], v[184:187], v[62:65]
	s_barrier
	s_add_u32 s100, s10, 0x80000
	s_addc_u32 s101, s11, 0
	ds_read_b128 v[66:69], v234
	ds_read_b128 v[70:73], v234 offset:1024
	ds_read_b128 v[74:77], v234 offset:2048
	ds_read_b128 v[78:81], v234 offset:3072
	ds_read_b128 v[82:85], v235
	ds_read_b128 v[86:89], v235 offset:1024
	ds_read_b128 v[170:173], v235 offset:2048
	ds_read_b128 v[184:187], v235 offset:3072
	ds_read_b128 v[90:93], v192 offset:32768
	ds_read_b128 v[94:97], v192 offset:33792
	ds_read_b128 v[194:197], v192 offset:34816
	ds_read_b128 v[198:201], v192 offset:35840
	ds_read_b128 v[202:205], v192 offset:36864
	s_mov_b32 m0, s43
	ds_read_b128 v[206:209], v192 offset:37888
	global_load_lds_dwordx4 v168, s[100:101]
	s_mov_b32 m0, s44
	ds_read_b128 v[210:213], v192 offset:38912
	global_load_lds_dwordx4 v164, s[100:101]
	ds_read_b128 v[222:225], v192 offset:39936
	s_waitcnt vmcnt(8) lgkmcnt(0)
	s_barrier
	v_mfma_f32_16x16x32_bf16 v[150:153], v[66:69], v[90:93], v[150:153]
	v_mfma_f32_16x16x32_bf16 v[142:145], v[74:77], v[90:93], v[142:145]
	v_mfma_f32_16x16x32_bf16 v[134:137], v[66:69], v[194:197], v[134:137]
	v_mfma_f32_16x16x32_bf16 v[126:129], v[74:77], v[194:197], v[126:129]
	v_mfma_f32_16x16x32_bf16 v[118:121], v[66:69], v[202:205], v[118:121]
	v_mfma_f32_16x16x32_bf16 v[114:117], v[74:77], v[202:205], v[114:117]
	v_mfma_f32_16x16x32_bf16 v[110:113], v[66:69], v[210:213], v[110:113]
	v_mfma_f32_16x16x32_bf16 v[106:109], v[74:77], v[210:213], v[106:109]
	v_mfma_f32_16x16x32_bf16 v[150:153], v[70:73], v[94:97], v[150:153]
	v_mfma_f32_16x16x32_bf16 v[142:145], v[78:81], v[94:97], v[142:145]
	v_mfma_f32_16x16x32_bf16 v[134:137], v[70:73], v[198:201], v[134:137]
	v_mfma_f32_16x16x32_bf16 v[126:129], v[78:81], v[198:201], v[126:129]
	v_mfma_f32_16x16x32_bf16 v[118:121], v[70:73], v[206:209], v[118:121]
	v_mfma_f32_16x16x32_bf16 v[114:117], v[78:81], v[206:209], v[114:117]
	v_mfma_f32_16x16x32_bf16 v[110:113], v[70:73], v[222:225], v[110:113]
	v_mfma_f32_16x16x32_bf16 v[106:109], v[78:81], v[222:225], v[106:109]
	v_mfma_f32_16x16x32_bf16 v[158:161], v[82:85], v[90:93], v[158:161]
	v_mfma_f32_16x16x32_bf16 v[90:93], v[170:173], v[90:93], v[154:157]
	v_mfma_f32_16x16x32_bf16 v[154:157], v[184:187], v[94:97], v[90:93]
	v_mfma_f32_16x16x32_bf16 v[90:93], v[82:85], v[194:197], v[146:149]
	v_mfma_f32_16x16x32_bf16 v[146:149], v[86:89], v[198:201], v[90:93]
	v_mfma_f32_16x16x32_bf16 v[90:93], v[170:173], v[194:197], v[138:141]
	v_mfma_f32_16x16x32_bf16 v[138:141], v[184:187], v[198:201], v[90:93]
	v_mfma_f32_16x16x32_bf16 v[90:93], v[82:85], v[202:205], v[130:133]
	v_mfma_f32_16x16x32_bf16 v[130:133], v[86:89], v[206:209], v[90:93]
	v_mfma_f32_16x16x32_bf16 v[90:93], v[170:173], v[202:205], v[122:125]
	v_mfma_f32_16x16x32_bf16 v[122:125], v[184:187], v[206:209], v[90:93]
	v_mfma_f32_16x16x32_bf16 v[90:93], v[82:85], v[210:213], v[102:105]
	v_mfma_f32_16x16x32_bf16 v[102:105], v[86:89], v[222:225], v[90:93]
	v_mfma_f32_16x16x32_bf16 v[90:93], v[170:173], v[210:213], v[98:101]
	v_mfma_f32_16x16x32_bf16 v[158:161], v[86:89], v[94:97], v[158:161]
	v_mfma_f32_16x16x32_bf16 v[98:101], v[184:187], v[222:225], v[90:93]
	s_barrier
	ds_read_b128 v[90:93], v192 offset:49152
	s_add_i32 m0, s38, 0x17f80
	ds_read_b128 v[194:197], v192 offset:50176
	global_load_lds_dwordx4 v166, s[8:9] offset:128
	s_add_i32 m0, s38, 0x19f80
	ds_read_b128 v[198:201], v192 offset:51200
	global_load_lds_dwordx4 v162, s[8:9] offset:128
	s_add_i32 m0, s38, 0x1bf80
	ds_read_b128 v[202:205], v192 offset:52224
	global_load_lds_dwordx4 v166, s[52:53] offset:128
	s_add_i32 m0, s38, 0x1df80
	ds_read_b128 v[206:209], v192 offset:53248
	global_load_lds_dwordx4 v162, s[52:53] offset:128
	s_add_i32 m0, s46, 0xffffff80
	ds_read_b128 v[210:213], v192 offset:54272
	global_load_lds_dwordx4 v168, s[10:11] offset:128
	s_add_i32 m0, s47, 0xffffff80
	ds_read_b128 v[222:225], v192 offset:55296
	global_load_lds_dwordx4 v164, s[10:11] offset:128
	ds_read_b128 v[230:233], v192 offset:56320
	s_waitcnt vmcnt(8) lgkmcnt(0)
	s_barrier
	v_mfma_f32_16x16x32_bf16 v[58:61], v[66:69], v[90:93], v[58:61]
	v_mfma_f32_16x16x32_bf16 v[46:49], v[74:77], v[90:93], v[46:49]
	v_mfma_f32_16x16x32_bf16 v[38:41], v[66:69], v[198:201], v[38:41]
	v_mfma_f32_16x16x32_bf16 v[30:33], v[74:77], v[198:201], v[30:33]
	v_mfma_f32_16x16x32_bf16 v[22:25], v[66:69], v[206:209], v[22:25]
	v_mfma_f32_16x16x32_bf16 v[18:21], v[74:77], v[206:209], v[18:21]
	v_mfma_f32_16x16x32_bf16 v[8:11], v[66:69], v[222:225], v[8:11]
	v_mfma_f32_16x16x32_bf16 v[12:15], v[74:77], v[222:225], v[12:15]
	v_mfma_f32_16x16x32_bf16 v[58:61], v[70:73], v[194:197], v[58:61]
	v_mfma_f32_16x16x32_bf16 v[46:49], v[78:81], v[194:197], v[46:49]
	v_mfma_f32_16x16x32_bf16 v[38:41], v[70:73], v[202:205], v[38:41]
	v_mfma_f32_16x16x32_bf16 v[30:33], v[78:81], v[202:205], v[30:33]
	v_mfma_f32_16x16x32_bf16 v[22:25], v[70:73], v[210:213], v[22:25]
	v_mfma_f32_16x16x32_bf16 v[18:21], v[78:81], v[210:213], v[18:21]
	v_mfma_f32_16x16x32_bf16 v[8:11], v[70:73], v[230:233], v[8:11]
	v_mfma_f32_16x16x32_bf16 v[12:15], v[78:81], v[230:233], v[12:15]
	v_mfma_f32_16x16x32_bf16 v[54:57], v[82:85], v[90:93], v[54:57]
	v_mfma_f32_16x16x32_bf16 v[94:97], v[86:89], v[194:197], v[54:57]
	v_mfma_f32_16x16x32_bf16 v[54:57], v[170:173], v[90:93], v[62:65]
	v_mfma_f32_16x16x32_bf16 v[50:53], v[82:85], v[198:201], v[50:53]
	v_mfma_f32_16x16x32_bf16 v[42:45], v[170:173], v[198:201], v[42:45]
	v_mfma_f32_16x16x32_bf16 v[34:37], v[82:85], v[206:209], v[34:37]
	v_mfma_f32_16x16x32_bf16 v[26:29], v[170:173], v[206:209], v[26:29]
	v_mfma_f32_16x16x32_bf16 v[0:3], v[82:85], v[222:225], v[0:3]
	v_mfma_f32_16x16x32_bf16 v[4:7], v[170:173], v[222:225], v[4:7]
	v_mfma_f32_16x16x32_bf16 v[90:93], v[184:187], v[194:197], v[54:57]
	v_mfma_f32_16x16x32_bf16 v[50:53], v[86:89], v[202:205], v[50:53]
	v_mfma_f32_16x16x32_bf16 v[42:45], v[184:187], v[202:205], v[42:45]
	v_mfma_f32_16x16x32_bf16 v[34:37], v[86:89], v[210:213], v[34:37]
	v_mfma_f32_16x16x32_bf16 v[26:29], v[184:187], v[210:213], v[26:29]
	v_mfma_f32_16x16x32_bf16 v[0:3], v[86:89], v[230:233], v[0:3]
	v_mfma_f32_16x16x32_bf16 v[4:7], v[184:187], v[230:233], v[4:7]
	s_barrier
	s_add_i32 s51, s51, 2
	s_add_u32 s6, s6, 0x100
	s_addc_u32 s7, s7, 0
	s_add_u32 s30, s30, 0x100
	s_addc_u32 s31, s31, 0
	s_cmp_gt_u32 s51, 29
	s_cbranch_scc0 .LBB0_68
	s_and_b64 vcc, exec, s[16:17]
	s_cbranch_vccz .LBB0_71
	s_barrier

.LBB0_107:
	s_ashr_i32 s9, s8, 31
	s_lshl_b64 s[10:11], s[8:9], 20
	s_add_u32 s10, s20, s10
	s_addc_u32 s11, s21, s11
	s_and_b64 s[12:13], s[4:5], exec
	s_cselect_b32 s9, s11, s15
	s_cselect_b32 s40, s10, s14
	s_ashr_i32 s7, s6, 31
	s_lshl_b64 s[12:13], s[6:7], 20
	s_add_u32 s12, s22, s12
	s_addc_u32 s13, s23, s13
	s_and_b64 s[18:19], s[4:5], exec
	s_cselect_b32 s7, s13, s17
	s_cselect_b32 s41, s12, s16
	s_add_u32 s14, s14, 0x80080
	s_addc_u32 s15, s15, 0
	s_add_u32 s42, s16, 0x100
	v_mov_b32_e32 v0, 0
	s_addc_u32 s43, s17, 0
	s_mov_b32 s44, -2
	v_mov_b32_e32 v1, v0
	v_mov_b32_e32 v2, v0
	v_mov_b32_e32 v3, v0
	v_mov_b32_e32 v26, v0
	v_mov_b32_e32 v27, v0
	v_mov_b32_e32 v28, v0
	v_mov_b32_e32 v29, v0
	v_mov_b32_e32 v4, v0
	v_mov_b32_e32 v5, v0
	v_mov_b32_e32 v6, v0
	v_mov_b32_e32 v7, v0
	v_mov_b32_e32 v34, v0
	v_mov_b32_e32 v35, v0
	v_mov_b32_e32 v36, v0
	v_mov_b32_e32 v37, v0
	v_mov_b32_e32 v8, v0
	v_mov_b32_e32 v9, v0
	v_mov_b32_e32 v10, v0
	v_mov_b32_e32 v11, v0
	v_mov_b32_e32 v38, v0
	v_mov_b32_e32 v39, v0
	v_mov_b32_e32 v40, v0
	v_mov_b32_e32 v41, v0
	v_mov_b32_e32 v12, v0
	v_mov_b32_e32 v13, v0
	v_mov_b32_e32 v14, v0
	v_mov_b32_e32 v15, v0
	v_mov_b32_e32 v46, v0
	v_mov_b32_e32 v47, v0
	v_mov_b32_e32 v48, v0
	v_mov_b32_e32 v49, v0
	v_mov_b32_e32 v62, v0
	v_mov_b32_e32 v63, v0
	v_mov_b32_e32 v64, v0
	v_mov_b32_e32 v65, v0
	v_mov_b32_e32 v98, v0
	v_mov_b32_e32 v99, v0
	v_mov_b32_e32 v100, v0
	v_mov_b32_e32 v101, v0
	s_waitcnt vmcnt(0)
	v_mov_b32_e32 v70, v0
	v_mov_b32_e32 v71, v0
	v_mov_b32_e32 v72, v0
	v_mov_b32_e32 v73, v0
	v_mov_b32_e32 v102, v0
	v_mov_b32_e32 v103, v0
	v_mov_b32_e32 v104, v0
	v_mov_b32_e32 v105, v0
	v_mov_b32_e32 v74, v0
	v_mov_b32_e32 v75, v0
	v_mov_b32_e32 v76, v0
	v_mov_b32_e32 v77, v0
	v_mov_b32_e32 v106, v0
	v_mov_b32_e32 v107, v0
	v_mov_b32_e32 v108, v0
	v_mov_b32_e32 v109, v0
	v_mov_b32_e32 v78, v0
	v_mov_b32_e32 v79, v0
	v_mov_b32_e32 v80, v0
	v_mov_b32_e32 v81, v0
	v_mov_b32_e32 v110, v0
	v_mov_b32_e32 v111, v0
	v_mov_b32_e32 v112, v0
	v_mov_b32_e32 v113, v0
	v_mov_b32_e32 v18, v0
	v_mov_b32_e32 v19, v0
	v_mov_b32_e32 v20, v0
	v_mov_b32_e32 v21, v0
	v_mov_b32_e32 v50, v0
	v_mov_b32_e32 v51, v0
	v_mov_b32_e32 v52, v0
	v_mov_b32_e32 v53, v0
	v_mov_b32_e32 v22, v0
	v_mov_b32_e32 v23, v0
	v_mov_b32_e32 v24, v0
	v_mov_b32_e32 v25, v0
	v_mov_b32_e32 v54, v0
	v_mov_b32_e32 v55, v0
	v_mov_b32_e32 v56, v0
	v_mov_b32_e32 v57, v0
	v_mov_b32_e32 v30, v0
	v_mov_b32_e32 v31, v0
	v_mov_b32_e32 v32, v0
	v_mov_b32_e32 v33, v0
	v_mov_b32_e32 v58, v0
	v_mov_b32_e32 v59, v0
	v_mov_b32_e32 v60, v0
	v_mov_b32_e32 v61, v0
	v_mov_b32_e32 v42, v0
	v_mov_b32_e32 v43, v0
	v_mov_b32_e32 v44, v0
	v_mov_b32_e32 v45, v0
	v_mov_b32_e32 v66, v0
	v_mov_b32_e32 v67, v0
	v_mov_b32_e32 v68, v0
	v_mov_b32_e32 v69, v0
	v_mov_b32_e32 v82, v0
	v_mov_b32_e32 v83, v0
	v_mov_b32_e32 v84, v0
	v_mov_b32_e32 v85, v0
	v_mov_b32_e32 v114, v0
	v_mov_b32_e32 v115, v0
	v_mov_b32_e32 v116, v0
	v_mov_b32_e32 v117, v0
	v_mov_b32_e32 v86, v0
	v_mov_b32_e32 v87, v0
	v_mov_b32_e32 v88, v0
	v_mov_b32_e32 v89, v0
	v_mov_b32_e32 v118, v0
	v_mov_b32_e32 v119, v0
	v_mov_b32_e32 v120, v0
	v_mov_b32_e32 v121, v0
	v_mov_b32_e32 v90, v0
	v_mov_b32_e32 v91, v0
	v_mov_b32_e32 v92, v0
	v_mov_b32_e32 v93, v0
	v_mov_b32_e32 v122, v0
	v_mov_b32_e32 v123, v0
	v_mov_b32_e32 v124, v0
	v_mov_b32_e32 v125, v0
	v_mov_b32_e32 v94, v0
	v_mov_b32_e32 v95, v0
	v_mov_b32_e32 v96, v0
	v_mov_b32_e32 v97, v0
	v_mov_b32_e32 v126, v0
	v_mov_b32_e32 v127, v0
	v_mov_b32_e32 v128, v0
	v_mov_b32_e32 v129, v0
	v_add_u32_e32 v170, 0x10000, v207
	v_add_u32_e32 v171, 0x14000, v207
	v_add_u32_e32 v172, 0x18000, v207
	v_add_u32_e32 v173, 0x1c000, v207
.LBB0_108:
	s_add_u32 s16, s14, 0xfff80080
	s_addc_u32 s17, s15, -1
	s_cmp_eq_u32 s44, 28
	s_cselect_b32 s19, s9, s17
	s_cselect_b32 s18, s40, s16
	s_cselect_b32 s17, s7, s43
	s_cselect_b32 s16, s41, s42
	ds_read_b128 v[130:133], v170
	ds_read_b128 v[134:137], v170 offset:1024
	ds_read_b128 v[138:141], v170 offset:2048
	ds_read_b128 v[142:145], v170 offset:3072
	ds_read_b128 v[146:149], v171
	ds_read_b128 v[150:153], v171 offset:1024
	ds_read_b128 v[154:157], v171 offset:2048
	ds_read_b128 v[158:161], v171 offset:3072
	ds_read_b128 v[162:165], v208
	ds_read_b128 v[166:169], v208 offset:1024
	ds_read_b128 v[184:187], v208 offset:2048
	ds_read_b128 v[188:191], v208 offset:3072
	ds_read_b128 v[192:195], v208 offset:4096
	s_add_i32 m0, s25, 0xc000
	ds_read_b128 v[196:199], v208 offset:5120
	global_load_lds_dwordx4 v180, s[14:15]
	s_add_i32 m0, s25, 0xe000
	ds_read_b128 v[200:203], v208 offset:6144
	global_load_lds_dwordx4 v182, s[14:15]
	ds_read_b128 v[210:213], v208 offset:7168
	s_waitcnt vmcnt(8) lgkmcnt(0)
	s_barrier
	v_mfma_f32_16x16x32_bf16 v[126:129], v[130:133], v[162:165], v[126:129]
	v_mfma_f32_16x16x32_bf16 v[94:97], v[138:141], v[162:165], v[94:97]
	v_mfma_f32_16x16x32_bf16 v[122:125], v[130:133], v[184:187], v[122:125]
	v_mfma_f32_16x16x32_bf16 v[90:93], v[138:141], v[184:187], v[90:93]
	v_mfma_f32_16x16x32_bf16 v[118:121], v[130:133], v[192:195], v[118:121]
	v_mfma_f32_16x16x32_bf16 v[86:89], v[138:141], v[192:195], v[86:89]
	v_mfma_f32_16x16x32_bf16 v[114:117], v[130:133], v[200:203], v[114:117]
	v_mfma_f32_16x16x32_bf16 v[82:85], v[138:141], v[200:203], v[82:85]
	v_mfma_f32_16x16x32_bf16 v[126:129], v[134:137], v[166:169], v[126:129]
	v_mfma_f32_16x16x32_bf16 v[94:97], v[142:145], v[166:169], v[94:97]
	v_mfma_f32_16x16x32_bf16 v[122:125], v[134:137], v[188:191], v[122:125]
	v_mfma_f32_16x16x32_bf16 v[90:93], v[142:145], v[188:191], v[90:93]
	v_mfma_f32_16x16x32_bf16 v[118:121], v[134:137], v[196:199], v[118:121]
	v_mfma_f32_16x16x32_bf16 v[86:89], v[142:145], v[196:199], v[86:89]
	v_mfma_f32_16x16x32_bf16 v[114:117], v[134:137], v[210:213], v[114:117]
	v_mfma_f32_16x16x32_bf16 v[82:85], v[142:145], v[210:213], v[82:85]
	v_mfma_f32_16x16x32_bf16 v[66:69], v[146:149], v[162:165], v[66:69]
	v_mfma_f32_16x16x32_bf16 v[42:45], v[154:157], v[162:165], v[42:45]
	v_mfma_f32_16x16x32_bf16 v[58:61], v[146:149], v[184:187], v[58:61]
	v_mfma_f32_16x16x32_bf16 v[30:33], v[154:157], v[184:187], v[30:33]
	v_mfma_f32_16x16x32_bf16 v[54:57], v[146:149], v[192:195], v[54:57]
	v_mfma_f32_16x16x32_bf16 v[22:25], v[154:157], v[192:195], v[22:25]
	v_mfma_f32_16x16x32_bf16 v[50:53], v[146:149], v[200:203], v[50:53]
	v_mfma_f32_16x16x32_bf16 v[18:21], v[154:157], v[200:203], v[18:21]
	v_mfma_f32_16x16x32_bf16 v[66:69], v[150:153], v[166:169], v[66:69]
	v_mfma_f32_16x16x32_bf16 v[42:45], v[158:161], v[166:169], v[42:45]
	v_mfma_f32_16x16x32_bf16 v[58:61], v[150:153], v[188:191], v[58:61]
	v_mfma_f32_16x16x32_bf16 v[30:33], v[158:161], v[188:191], v[30:33]
	v_mfma_f32_16x16x32_bf16 v[54:57], v[150:153], v[196:199], v[54:57]
	v_mfma_f32_16x16x32_bf16 v[22:25], v[158:161], v[196:199], v[22:25]
	v_mfma_f32_16x16x32_bf16 v[50:53], v[150:153], v[210:213], v[50:53]
	v_mfma_f32_16x16x32_bf16 v[18:21], v[158:161], v[210:213], v[18:21]
	s_barrier
	ds_read_b128 v[162:165], v208 offset:16384
	s_add_i32 m0, s24, 0x10000
	ds_read_b128 v[166:169], v208 offset:17408
	global_load_lds_dwordx4 v178, s[16:17]
	s_add_i32 m0, s24, 0x12000
	s_add_u32 s46, s16, 0x80000
	s_addc_u32 s47, s17, 0
	ds_read_b128 v[184:187], v208 offset:18432
	global_load_lds_dwordx4 v176, s[16:17]
	s_add_i32 m0, s24, 0x14000
	ds_read_b128 v[188:191], v208 offset:19456
	global_load_lds_dwordx4 v178, s[46:47]
	s_add_i32 m0, s24, 0x16000
	ds_read_b128 v[192:195], v208 offset:20480
	global_load_lds_dwordx4 v176, s[46:47]
	s_mov_b32 m0, s25
	ds_read_b128 v[196:199], v208 offset:21504
	global_load_lds_dwordx4 v178, s[18:19]
	s_mov_b32 m0, s26
	ds_read_b128 v[200:203], v208 offset:22528
	global_load_lds_dwordx4 v176, s[18:19]
	ds_read_b128 v[210:213], v208 offset:23552
	s_waitcnt vmcnt(8) lgkmcnt(0)
	s_barrier
	v_mfma_f32_16x16x32_bf16 v[110:113], v[130:133], v[162:165], v[110:113]
	v_mfma_f32_16x16x32_bf16 v[78:81], v[138:141], v[162:165], v[78:81]
	v_mfma_f32_16x16x32_bf16 v[106:109], v[130:133], v[184:187], v[106:109]
	v_mfma_f32_16x16x32_bf16 v[74:77], v[138:141], v[184:187], v[74:77]
	v_mfma_f32_16x16x32_bf16 v[102:105], v[130:133], v[192:195], v[102:105]
	v_mfma_f32_16x16x32_bf16 v[70:73], v[138:141], v[192:195], v[70:73]
	v_mfma_f32_16x16x32_bf16 v[98:101], v[130:133], v[200:203], v[98:101]
	v_mfma_f32_16x16x32_bf16 v[62:65], v[138:141], v[200:203], v[62:65]
	v_mfma_f32_16x16x32_bf16 v[110:113], v[134:137], v[166:169], v[110:113]
	v_mfma_f32_16x16x32_bf16 v[78:81], v[142:145], v[166:169], v[78:81]
	v_mfma_f32_16x16x32_bf16 v[106:109], v[134:137], v[188:191], v[106:109]
	v_mfma_f32_16x16x32_bf16 v[74:77], v[142:145], v[188:191], v[74:77]
	v_mfma_f32_16x16x32_bf16 v[102:105], v[134:137], v[196:199], v[102:105]
	v_mfma_f32_16x16x32_bf16 v[70:73], v[142:145], v[196:199], v[70:73]
	v_mfma_f32_16x16x32_bf16 v[98:101], v[134:137], v[210:213], v[98:101]
	v_mfma_f32_16x16x32_bf16 v[62:65], v[142:145], v[210:213], v[62:65]
	v_mfma_f32_16x16x32_bf16 v[46:49], v[146:149], v[162:165], v[46:49]
	v_mfma_f32_16x16x32_bf16 v[12:15], v[154:157], v[162:165], v[12:15]
	v_mfma_f32_16x16x32_bf16 v[38:41], v[146:149], v[184:187], v[38:41]
	v_mfma_f32_16x16x32_bf16 v[8:11], v[154:157], v[184:187], v[8:11]
	v_mfma_f32_16x16x32_bf16 v[34:37], v[146:149], v[192:195], v[34:37]
	v_mfma_f32_16x16x32_bf16 v[4:7], v[154:157], v[192:195], v[4:7]
	v_mfma_f32_16x16x32_bf16 v[26:29], v[146:149], v[200:203], v[26:29]
	v_mfma_f32_16x16x32_bf16 v[0:3], v[154:157], v[200:203], v[0:3]
	v_mfma_f32_16x16x32_bf16 v[46:49], v[150:153], v[166:169], v[46:49]
	v_mfma_f32_16x16x32_bf16 v[12:15], v[158:161], v[166:169], v[12:15]
	v_mfma_f32_16x16x32_bf16 v[38:41], v[150:153], v[188:191], v[38:41]
	v_mfma_f32_16x16x32_bf16 v[8:11], v[158:161], v[188:191], v[8:11]
	v_mfma_f32_16x16x32_bf16 v[34:37], v[150:153], v[196:199], v[34:37]
	v_mfma_f32_16x16x32_bf16 v[4:7], v[158:161], v[196:199], v[4:7]
	v_mfma_f32_16x16x32_bf16 v[26:29], v[150:153], v[210:213], v[26:29]
	v_mfma_f32_16x16x32_bf16 v[0:3], v[158:161], v[210:213], v[0:3]
	s_barrier
	s_add_u32 s100, s18, 0x80000
	s_addc_u32 s101, s19, 0
	ds_read_b128 v[130:133], v172
	ds_read_b128 v[134:137], v172 offset:1024
	ds_read_b128 v[138:141], v172 offset:2048
	ds_read_b128 v[142:145], v172 offset:3072
	ds_read_b128 v[146:149], v173
	ds_read_b128 v[150:153], v173 offset:1024
	ds_read_b128 v[154:157], v173 offset:2048
	ds_read_b128 v[158:161], v173 offset:3072
	ds_read_b128 v[162:165], v208 offset:32768
	ds_read_b128 v[166:169], v208 offset:33792
	ds_read_b128 v[184:187], v208 offset:34816
	ds_read_b128 v[188:191], v208 offset:35840
	ds_read_b128 v[192:195], v208 offset:36864
	s_mov_b32 m0, s27
	ds_read_b128 v[196:199], v208 offset:37888
	global_load_lds_dwordx4 v178, s[100:101]
	s_mov_b32 m0, s28
	ds_read_b128 v[200:203], v208 offset:38912
	global_load_lds_dwordx4 v176, s[100:101]
	ds_read_b128 v[210:213], v208 offset:39936
	s_waitcnt vmcnt(8) lgkmcnt(0)
	s_barrier
	v_mfma_f32_16x16x32_bf16 v[126:129], v[130:133], v[162:165], v[126:129]
	v_mfma_f32_16x16x32_bf16 v[94:97], v[138:141], v[162:165], v[94:97]
	v_mfma_f32_16x16x32_bf16 v[122:125], v[130:133], v[184:187], v[122:125]
	v_mfma_f32_16x16x32_bf16 v[90:93], v[138:141], v[184:187], v[90:93]
	v_mfma_f32_16x16x32_bf16 v[118:121], v[130:133], v[192:195], v[118:121]
	v_mfma_f32_16x16x32_bf16 v[86:89], v[138:141], v[192:195], v[86:89]
	v_mfma_f32_16x16x32_bf16 v[114:117], v[130:133], v[200:203], v[114:117]
	v_mfma_f32_16x16x32_bf16 v[82:85], v[138:141], v[200:203], v[82:85]
	v_mfma_f32_16x16x32_bf16 v[126:129], v[134:137], v[166:169], v[126:129]
	v_mfma_f32_16x16x32_bf16 v[94:97], v[142:145], v[166:169], v[94:97]
	v_mfma_f32_16x16x32_bf16 v[122:125], v[134:137], v[188:191], v[122:125]
	v_mfma_f32_16x16x32_bf16 v[90:93], v[142:145], v[188:191], v[90:93]
	v_mfma_f32_16x16x32_bf16 v[118:121], v[134:137], v[196:199], v[118:121]
	v_mfma_f32_16x16x32_bf16 v[86:89], v[142:145], v[196:199], v[86:89]
	v_mfma_f32_16x16x32_bf16 v[114:117], v[134:137], v[210:213], v[114:117]
	v_mfma_f32_16x16x32_bf16 v[82:85], v[142:145], v[210:213], v[82:85]
	v_mfma_f32_16x16x32_bf16 v[66:69], v[146:149], v[162:165], v[66:69]
	v_mfma_f32_16x16x32_bf16 v[42:45], v[154:157], v[162:165], v[42:45]
	v_mfma_f32_16x16x32_bf16 v[58:61], v[146:149], v[184:187], v[58:61]
	v_mfma_f32_16x16x32_bf16 v[30:33], v[154:157], v[184:187], v[30:33]
	v_mfma_f32_16x16x32_bf16 v[54:57], v[146:149], v[192:195], v[54:57]
	v_mfma_f32_16x16x32_bf16 v[22:25], v[154:157], v[192:195], v[22:25]
	v_mfma_f32_16x16x32_bf16 v[50:53], v[146:149], v[200:203], v[50:53]
	v_mfma_f32_16x16x32_bf16 v[18:21], v[154:157], v[200:203], v[18:21]
	v_mfma_f32_16x16x32_bf16 v[66:69], v[150:153], v[166:169], v[66:69]
	v_mfma_f32_16x16x32_bf16 v[42:45], v[158:161], v[166:169], v[42:45]
	v_mfma_f32_16x16x32_bf16 v[58:61], v[150:153], v[188:191], v[58:61]
	v_mfma_f32_16x16x32_bf16 v[30:33], v[158:161], v[188:191], v[30:33]
	v_mfma_f32_16x16x32_bf16 v[54:57], v[150:153], v[196:199], v[54:57]
	v_mfma_f32_16x16x32_bf16 v[22:25], v[158:161], v[196:199], v[22:25]
	v_mfma_f32_16x16x32_bf16 v[50:53], v[150:153], v[210:213], v[50:53]
	v_mfma_f32_16x16x32_bf16 v[18:21], v[158:161], v[210:213], v[18:21]
	s_barrier
	ds_read_b128 v[162:165], v208 offset:49152
	s_add_i32 m0, s24, 0x17f80
	ds_read_b128 v[166:169], v208 offset:50176
	global_load_lds_dwordx4 v178, s[16:17] offset:128
	s_add_i32 m0, s24, 0x19f80
	ds_read_b128 v[184:187], v208 offset:51200
	global_load_lds_dwordx4 v176, s[16:17] offset:128
	s_add_i32 m0, s24, 0x1bf80
	ds_read_b128 v[188:191], v208 offset:52224
	global_load_lds_dwordx4 v178, s[46:47] offset:128
	s_add_i32 m0, s24, 0x1df80
	ds_read_b128 v[192:195], v208 offset:53248
	global_load_lds_dwordx4 v176, s[46:47] offset:128
	s_add_i32 m0, s35, 0xffffff80
	ds_read_b128 v[196:199], v208 offset:54272
	global_load_lds_dwordx4 v178, s[18:19] offset:128
	s_add_i32 m0, s36, 0xffffff80
	ds_read_b128 v[200:203], v208 offset:55296
	global_load_lds_dwordx4 v176, s[18:19] offset:128
	ds_read_b128 v[210:213], v208 offset:56320
	s_waitcnt vmcnt(8) lgkmcnt(0)
	s_barrier
	v_mfma_f32_16x16x32_bf16 v[110:113], v[130:133], v[162:165], v[110:113]
	v_mfma_f32_16x16x32_bf16 v[78:81], v[138:141], v[162:165], v[78:81]
	v_mfma_f32_16x16x32_bf16 v[106:109], v[130:133], v[184:187], v[106:109]
	v_mfma_f32_16x16x32_bf16 v[74:77], v[138:141], v[184:187], v[74:77]
	v_mfma_f32_16x16x32_bf16 v[102:105], v[130:133], v[192:195], v[102:105]
	v_mfma_f32_16x16x32_bf16 v[70:73], v[138:141], v[192:195], v[70:73]
	v_mfma_f32_16x16x32_bf16 v[98:101], v[130:133], v[200:203], v[98:101]
	v_mfma_f32_16x16x32_bf16 v[62:65], v[138:141], v[200:203], v[62:65]
	v_mfma_f32_16x16x32_bf16 v[110:113], v[134:137], v[166:169], v[110:113]
	v_mfma_f32_16x16x32_bf16 v[78:81], v[142:145], v[166:169], v[78:81]
	v_mfma_f32_16x16x32_bf16 v[106:109], v[134:137], v[188:191], v[106:109]
	v_mfma_f32_16x16x32_bf16 v[74:77], v[142:145], v[188:191], v[74:77]
	v_mfma_f32_16x16x32_bf16 v[102:105], v[134:137], v[196:199], v[102:105]
	v_mfma_f32_16x16x32_bf16 v[70:73], v[142:145], v[196:199], v[70:73]
	v_mfma_f32_16x16x32_bf16 v[98:101], v[134:137], v[210:213], v[98:101]
	v_mfma_f32_16x16x32_bf16 v[62:65], v[142:145], v[210:213], v[62:65]
	v_mfma_f32_16x16x32_bf16 v[46:49], v[146:149], v[162:165], v[46:49]
	v_mfma_f32_16x16x32_bf16 v[12:15], v[154:157], v[162:165], v[12:15]
	v_mfma_f32_16x16x32_bf16 v[38:41], v[146:149], v[184:187], v[38:41]
	v_mfma_f32_16x16x32_bf16 v[8:11], v[154:157], v[184:187], v[8:11]
	v_mfma_f32_16x16x32_bf16 v[34:37], v[146:149], v[192:195], v[34:37]
	v_mfma_f32_16x16x32_bf16 v[4:7], v[154:157], v[192:195], v[4:7]
	v_mfma_f32_16x16x32_bf16 v[26:29], v[146:149], v[200:203], v[26:29]
	v_mfma_f32_16x16x32_bf16 v[0:3], v[154:157], v[200:203], v[0:3]
	v_mfma_f32_16x16x32_bf16 v[46:49], v[150:153], v[166:169], v[46:49]
	v_mfma_f32_16x16x32_bf16 v[12:15], v[158:161], v[166:169], v[12:15]
	v_mfma_f32_16x16x32_bf16 v[38:41], v[150:153], v[188:191], v[38:41]
	v_mfma_f32_16x16x32_bf16 v[8:11], v[158:161], v[188:191], v[8:11]
	v_mfma_f32_16x16x32_bf16 v[34:37], v[150:153], v[196:199], v[34:37]
	v_mfma_f32_16x16x32_bf16 v[4:7], v[158:161], v[196:199], v[4:7]
	v_mfma_f32_16x16x32_bf16 v[26:29], v[150:153], v[210:213], v[26:29]
	v_mfma_f32_16x16x32_bf16 v[0:3], v[158:161], v[210:213], v[0:3]
	s_barrier
	s_add_i32 s44, s44, 2
	s_add_u32 s14, s14, 0x100
	s_addc_u32 s15, s15, 0
	s_add_u32 s42, s42, 0x100
	s_addc_u32 s43, s43, 0
	s_cmp_gt_u32 s44, 29
	s_cbranch_scc0 .LBB0_108
	s_and_b64 vcc, exec, s[2:3]
	s_movk_i32 s44, 0x1000
	s_cbranch_vccz .LBB0_111
	s_barrier

.LBB0_551:
	s_ashr_i32 s19, s18, 31
	s_lshl_b64 s[20:21], s[18:19], 18
	s_add_u32 s17, s0, s20
	s_addc_u32 s19, s1, s21
	s_cmp_gt_i32 s16, 1
	s_cselect_b32 s20, 0x2000000, 0
	s_add_u32 s20, s17, s20
	s_addc_u32 s21, s19, 0
	s_and_b64 s[22:23], s[4:5], exec
	s_cselect_b32 s19, s21, s7
	s_cselect_b32 s42, s20, s6
	s_ashr_i32 s17, s16, 31
	s_lshl_b64 s[22:23], s[16:17], 18
	s_add_u32 s22, s28, s22
	s_addc_u32 s23, s29, s23
	s_and_b64 s[24:25], s[4:5], exec
	s_cselect_b32 s17, s23, s9
	s_cselect_b32 s43, s22, s8
	s_add_u32 s6, s6, 0x20080
	s_addc_u32 s7, s7, 0
	s_add_u32 s44, s8, 0x100
	v_mov_b32_e32 v0, 0
	s_addc_u32 s45, s9, 0
	s_mov_b32 s46, -2
	v_mov_b32_e32 v1, v0
	v_mov_b32_e32 v2, v0
	v_mov_b32_e32 v3, v0
	v_mov_b32_e32 v4, v0
	v_mov_b32_e32 v5, v0
	v_mov_b32_e32 v6, v0
	v_mov_b32_e32 v7, v0
	v_mov_b32_e32 v8, v0
	v_mov_b32_e32 v9, v0
	v_mov_b32_e32 v10, v0
	v_mov_b32_e32 v11, v0
	v_mov_b32_e32 v12, v0
	v_mov_b32_e32 v13, v0
	v_mov_b32_e32 v14, v0
	v_mov_b32_e32 v15, v0
	v_mov_b32_e32 v18, v0
	v_mov_b32_e32 v19, v0
	v_mov_b32_e32 v20, v0
	v_mov_b32_e32 v21, v0
	v_mov_b32_e32 v22, v0
	v_mov_b32_e32 v23, v0
	v_mov_b32_e32 v24, v0
	v_mov_b32_e32 v25, v0
	v_mov_b32_e32 v26, v0
	v_mov_b32_e32 v27, v0
	v_mov_b32_e32 v28, v0
	v_mov_b32_e32 v29, v0
	v_mov_b32_e32 v30, v0
	v_mov_b32_e32 v31, v0
	v_mov_b32_e32 v32, v0
	v_mov_b32_e32 v33, v0
	s_waitcnt vmcnt(0)
	v_mov_b32_e32 v78, v0
	v_mov_b32_e32 v79, v0
	v_mov_b32_e32 v80, v0
	v_mov_b32_e32 v81, v0
	v_mov_b32_e32 v82, v0
	v_mov_b32_e32 v83, v0
	v_mov_b32_e32 v84, v0
	v_mov_b32_e32 v85, v0
	v_mov_b32_e32 v90, v0
	v_mov_b32_e32 v91, v0
	v_mov_b32_e32 v92, v0
	v_mov_b32_e32 v93, v0
	v_mov_b32_e32 v94, v0
	v_mov_b32_e32 v95, v0
	v_mov_b32_e32 v96, v0
	v_mov_b32_e32 v97, v0
	v_mov_b32_e32 v98, v0
	v_mov_b32_e32 v99, v0
	v_mov_b32_e32 v100, v0
	v_mov_b32_e32 v101, v0
	v_mov_b32_e32 v102, v0
	v_mov_b32_e32 v103, v0
	v_mov_b32_e32 v104, v0
	v_mov_b32_e32 v105, v0
	v_mov_b32_e32 v106, v0
	v_mov_b32_e32 v107, v0
	v_mov_b32_e32 v108, v0
	v_mov_b32_e32 v109, v0
	v_mov_b32_e32 v110, v0
	v_mov_b32_e32 v111, v0
	v_mov_b32_e32 v112, v0
	v_mov_b32_e32 v113, v0
	v_mov_b32_e32 v34, v0
	v_mov_b32_e32 v35, v0
	v_mov_b32_e32 v36, v0
	v_mov_b32_e32 v37, v0
	v_mov_b32_e32 v38, v0
	v_mov_b32_e32 v39, v0
	v_mov_b32_e32 v40, v0
	v_mov_b32_e32 v41, v0
	v_mov_b32_e32 v42, v0
	v_mov_b32_e32 v43, v0
	v_mov_b32_e32 v44, v0
	v_mov_b32_e32 v45, v0
	v_mov_b32_e32 v46, v0
	v_mov_b32_e32 v47, v0
	v_mov_b32_e32 v48, v0
	v_mov_b32_e32 v49, v0
	v_mov_b32_e32 v50, v0
	v_mov_b32_e32 v51, v0
	v_mov_b32_e32 v52, v0
	v_mov_b32_e32 v53, v0
	v_mov_b32_e32 v54, v0
	v_mov_b32_e32 v55, v0
	v_mov_b32_e32 v56, v0
	v_mov_b32_e32 v57, v0
	v_mov_b32_e32 v62, v0
	v_mov_b32_e32 v63, v0
	v_mov_b32_e32 v64, v0
	v_mov_b32_e32 v65, v0
	v_mov_b32_e32 v66, v0
	v_mov_b32_e32 v67, v0
	v_mov_b32_e32 v68, v0
	v_mov_b32_e32 v69, v0
	v_mov_b32_e32 v114, v0
	v_mov_b32_e32 v115, v0
	v_mov_b32_e32 v116, v0
	v_mov_b32_e32 v117, v0
	v_mov_b32_e32 v118, v0
	v_mov_b32_e32 v119, v0
	v_mov_b32_e32 v120, v0
	v_mov_b32_e32 v121, v0
	v_mov_b32_e32 v130, v0
	v_mov_b32_e32 v131, v0
	v_mov_b32_e32 v132, v0
	v_mov_b32_e32 v133, v0
	v_mov_b32_e32 v134, v0
	v_mov_b32_e32 v135, v0
	v_mov_b32_e32 v136, v0
	v_mov_b32_e32 v137, v0
	v_mov_b32_e32 v138, v0
	v_mov_b32_e32 v139, v0
	v_mov_b32_e32 v140, v0
	v_mov_b32_e32 v141, v0
	v_mov_b32_e32 v142, v0
	v_mov_b32_e32 v143, v0
	v_mov_b32_e32 v144, v0
	v_mov_b32_e32 v145, v0
	v_mov_b32_e32 v146, v0
	v_mov_b32_e32 v147, v0
	v_mov_b32_e32 v148, v0
	v_mov_b32_e32 v149, v0
	v_mov_b32_e32 v150, v0
	v_mov_b32_e32 v151, v0
	v_mov_b32_e32 v152, v0
	v_mov_b32_e32 v153, v0
	v_add_u32_e32 v168, 0x10000, v184
	v_add_u32_e32 v169, 0x14000, v184
	v_add_u32_e32 v170, 0x18000, v184
	v_add_u32_e32 v171, 0x1c000, v184
.LBB0_552:
	s_add_u32 s8, s6, 0xfffe0080
	s_addc_u32 s9, s7, -1
	s_cmp_eq_u32 s46, 4
	s_cselect_b32 s25, s19, s9
	s_cselect_b32 s24, s42, s8
	s_cselect_b32 s9, s17, s45
	s_cselect_b32 s8, s43, s44
	ds_read_b128 v[58:61], v168
	ds_read_b128 v[70:73], v168 offset:1024
	ds_read_b128 v[74:77], v168 offset:2048
	ds_read_b128 v[86:89], v168 offset:3072
	ds_read_b128 v[122:125], v169
	ds_read_b128 v[126:129], v169 offset:1024
	ds_read_b128 v[154:157], v169 offset:2048
	ds_read_b128 v[176:179], v169 offset:3072
	ds_read_b128 v[186:189], v185
	ds_read_b128 v[190:193], v185 offset:1024
	ds_read_b128 v[194:197], v185 offset:2048
	ds_read_b128 v[198:201], v185 offset:3072
	ds_read_b128 v[202:205], v185 offset:4096
	s_add_i32 m0, s31, 0xc000
	ds_read_b128 v[206:209], v185 offset:5120
	global_load_lds_dwordx4 v164, s[6:7]
	s_add_i32 m0, s31, 0xe000
	ds_read_b128 v[210:213], v185 offset:6144
	global_load_lds_dwordx4 v166, s[6:7]
	ds_read_b128 v[230:233], v185 offset:7168
	s_waitcnt vmcnt(8) lgkmcnt(0)
	s_barrier
	v_mfma_f32_16x16x32_bf16 v[150:153], v[58:61], v[186:189], v[150:153]
	v_mfma_f32_16x16x32_bf16 v[146:149], v[74:77], v[186:189], v[146:149]
	v_mfma_f32_16x16x32_bf16 v[142:145], v[58:61], v[194:197], v[142:145]
	v_mfma_f32_16x16x32_bf16 v[138:141], v[74:77], v[194:197], v[138:141]
	v_mfma_f32_16x16x32_bf16 v[134:137], v[58:61], v[202:205], v[134:137]
	v_mfma_f32_16x16x32_bf16 v[130:133], v[74:77], v[202:205], v[130:133]
	v_mfma_f32_16x16x32_bf16 v[118:121], v[58:61], v[210:213], v[118:121]
	v_mfma_f32_16x16x32_bf16 v[114:117], v[74:77], v[210:213], v[114:117]
	v_mfma_f32_16x16x32_bf16 v[150:153], v[70:73], v[190:193], v[150:153]
	v_mfma_f32_16x16x32_bf16 v[146:149], v[86:89], v[190:193], v[146:149]
	v_mfma_f32_16x16x32_bf16 v[142:145], v[70:73], v[198:201], v[142:145]
	v_mfma_f32_16x16x32_bf16 v[138:141], v[86:89], v[198:201], v[138:141]
	v_mfma_f32_16x16x32_bf16 v[134:137], v[70:73], v[206:209], v[134:137]
	v_mfma_f32_16x16x32_bf16 v[130:133], v[86:89], v[206:209], v[130:133]
	v_mfma_f32_16x16x32_bf16 v[118:121], v[70:73], v[230:233], v[118:121]
	v_mfma_f32_16x16x32_bf16 v[114:117], v[86:89], v[230:233], v[114:117]
	v_mfma_f32_16x16x32_bf16 v[66:69], v[122:125], v[186:189], v[66:69]
	v_mfma_f32_16x16x32_bf16 v[62:65], v[154:157], v[186:189], v[62:65]
	v_mfma_f32_16x16x32_bf16 v[54:57], v[122:125], v[194:197], v[54:57]
	v_mfma_f32_16x16x32_bf16 v[50:53], v[154:157], v[194:197], v[50:53]
	v_mfma_f32_16x16x32_bf16 v[46:49], v[122:125], v[202:205], v[46:49]
	v_mfma_f32_16x16x32_bf16 v[42:45], v[154:157], v[202:205], v[42:45]
	v_mfma_f32_16x16x32_bf16 v[38:41], v[122:125], v[210:213], v[38:41]
	v_mfma_f32_16x16x32_bf16 v[34:37], v[154:157], v[210:213], v[34:37]
	v_mfma_f32_16x16x32_bf16 v[66:69], v[126:129], v[190:193], v[66:69]
	v_mfma_f32_16x16x32_bf16 v[62:65], v[176:179], v[190:193], v[62:65]
	v_mfma_f32_16x16x32_bf16 v[54:57], v[126:129], v[198:201], v[54:57]
	v_mfma_f32_16x16x32_bf16 v[50:53], v[176:179], v[198:201], v[50:53]
	v_mfma_f32_16x16x32_bf16 v[46:49], v[126:129], v[206:209], v[46:49]
	v_mfma_f32_16x16x32_bf16 v[42:45], v[176:179], v[206:209], v[42:45]
	v_mfma_f32_16x16x32_bf16 v[38:41], v[126:129], v[230:233], v[38:41]
	v_mfma_f32_16x16x32_bf16 v[34:37], v[176:179], v[230:233], v[34:37]
	s_barrier
	ds_read_b128 v[186:189], v185 offset:16384
	s_add_i32 m0, s30, 0x10000
	ds_read_b128 v[190:193], v185 offset:17408
	global_load_lds_dwordx4 v16, s[8:9]
	s_add_i32 m0, s30, 0x12000
	s_add_u32 s48, s8, 0x20000
	s_addc_u32 s49, s9, 0
	ds_read_b128 v[194:197], v185 offset:18432
	global_load_lds_dwordx4 v158, s[8:9]
	s_add_i32 m0, s30, 0x14000
	ds_read_b128 v[198:201], v185 offset:19456
	global_load_lds_dwordx4 v16, s[48:49]
	s_add_i32 m0, s30, 0x16000
	ds_read_b128 v[202:205], v185 offset:20480
	global_load_lds_dwordx4 v158, s[48:49]
	s_mov_b32 m0, s31
	ds_read_b128 v[206:209], v185 offset:21504
	global_load_lds_dwordx4 v162, s[24:25]
	s_mov_b32 m0, s34
	ds_read_b128 v[210:213], v185 offset:22528
	global_load_lds_dwordx4 v160, s[24:25]
	ds_read_b128 v[230:233], v185 offset:23552
	s_waitcnt vmcnt(8) lgkmcnt(0)
	s_barrier
	v_mfma_f32_16x16x32_bf16 v[110:113], v[58:61], v[186:189], v[110:113]
	v_mfma_f32_16x16x32_bf16 v[106:109], v[74:77], v[186:189], v[106:109]
	v_mfma_f32_16x16x32_bf16 v[102:105], v[58:61], v[194:197], v[102:105]
	v_mfma_f32_16x16x32_bf16 v[98:101], v[74:77], v[194:197], v[98:101]
	v_mfma_f32_16x16x32_bf16 v[94:97], v[58:61], v[202:205], v[94:97]
	v_mfma_f32_16x16x32_bf16 v[90:93], v[74:77], v[202:205], v[90:93]
	v_mfma_f32_16x16x32_bf16 v[58:61], v[58:61], v[210:213], v[82:85]
	v_mfma_f32_16x16x32_bf16 v[110:113], v[70:73], v[190:193], v[110:113]
	v_mfma_f32_16x16x32_bf16 v[106:109], v[86:89], v[190:193], v[106:109]
	v_mfma_f32_16x16x32_bf16 v[102:105], v[70:73], v[198:201], v[102:105]
	v_mfma_f32_16x16x32_bf16 v[98:101], v[86:89], v[198:201], v[98:101]
	v_mfma_f32_16x16x32_bf16 v[94:97], v[70:73], v[206:209], v[94:97]
	v_mfma_f32_16x16x32_bf16 v[90:93], v[86:89], v[206:209], v[90:93]
	v_mfma_f32_16x16x32_bf16 v[58:61], v[70:73], v[230:233], v[58:61]
	v_mfma_f32_16x16x32_bf16 v[70:73], v[74:77], v[210:213], v[78:81]
	v_mfma_f32_16x16x32_bf16 v[70:73], v[86:89], v[230:233], v[70:73]
	v_mfma_f32_16x16x32_bf16 v[30:33], v[122:125], v[186:189], v[30:33]
	v_mfma_f32_16x16x32_bf16 v[26:29], v[154:157], v[186:189], v[26:29]
	v_mfma_f32_16x16x32_bf16 v[22:25], v[122:125], v[194:197], v[22:25]
	v_mfma_f32_16x16x32_bf16 v[18:21], v[154:157], v[194:197], v[18:21]
	v_mfma_f32_16x16x32_bf16 v[12:15], v[122:125], v[202:205], v[12:15]
	v_mfma_f32_16x16x32_bf16 v[8:11], v[154:157], v[202:205], v[8:11]
	v_mfma_f32_16x16x32_bf16 v[4:7], v[122:125], v[210:213], v[4:7]
	v_mfma_f32_16x16x32_bf16 v[0:3], v[154:157], v[210:213], v[0:3]
	v_mfma_f32_16x16x32_bf16 v[30:33], v[126:129], v[190:193], v[30:33]
	v_mfma_f32_16x16x32_bf16 v[26:29], v[176:179], v[190:193], v[26:29]
	v_mfma_f32_16x16x32_bf16 v[22:25], v[126:129], v[198:201], v[22:25]
	v_mfma_f32_16x16x32_bf16 v[18:21], v[176:179], v[198:201], v[18:21]
	v_mfma_f32_16x16x32_bf16 v[12:15], v[126:129], v[206:209], v[12:15]
	v_mfma_f32_16x16x32_bf16 v[8:11], v[176:179], v[206:209], v[8:11]
	v_mfma_f32_16x16x32_bf16 v[4:7], v[126:129], v[230:233], v[4:7]
	v_mfma_f32_16x16x32_bf16 v[0:3], v[176:179], v[230:233], v[0:3]
	s_barrier
	s_add_u32 s100, s24, 0x20000
	s_addc_u32 s101, s25, 0
	ds_read_b128 v[74:77], v170
	ds_read_b128 v[78:81], v170 offset:1024
	ds_read_b128 v[86:89], v170 offset:2048
	ds_read_b128 v[122:125], v170 offset:3072
	ds_read_b128 v[126:129], v171
	ds_read_b128 v[154:157], v171 offset:1024
	ds_read_b128 v[176:179], v171 offset:2048
	ds_read_b128 v[186:189], v171 offset:3072
	ds_read_b128 v[82:85], v185 offset:32768
	ds_read_b128 v[190:193], v185 offset:33792
	ds_read_b128 v[194:197], v185 offset:34816
	ds_read_b128 v[198:201], v185 offset:35840
	ds_read_b128 v[202:205], v185 offset:36864
	s_mov_b32 m0, s35
	ds_read_b128 v[206:209], v185 offset:37888
	global_load_lds_dwordx4 v162, s[100:101]
	s_mov_b32 m0, s36
	ds_read_b128 v[210:213], v185 offset:38912
	global_load_lds_dwordx4 v160, s[100:101]
	ds_read_b128 v[230:233], v185 offset:39936
	s_waitcnt vmcnt(8) lgkmcnt(0)
	s_barrier
	v_mfma_f32_16x16x32_bf16 v[150:153], v[74:77], v[82:85], v[150:153]
	v_mfma_f32_16x16x32_bf16 v[146:149], v[86:89], v[82:85], v[146:149]
	v_mfma_f32_16x16x32_bf16 v[142:145], v[74:77], v[194:197], v[142:145]
	v_mfma_f32_16x16x32_bf16 v[138:141], v[86:89], v[194:197], v[138:141]
	v_mfma_f32_16x16x32_bf16 v[134:137], v[74:77], v[202:205], v[134:137]
	v_mfma_f32_16x16x32_bf16 v[130:133], v[86:89], v[202:205], v[130:133]
	v_mfma_f32_16x16x32_bf16 v[118:121], v[74:77], v[210:213], v[118:121]
	v_mfma_f32_16x16x32_bf16 v[114:117], v[86:89], v[210:213], v[114:117]
	v_mfma_f32_16x16x32_bf16 v[150:153], v[78:81], v[190:193], v[150:153]
	v_mfma_f32_16x16x32_bf16 v[146:149], v[122:125], v[190:193], v[146:149]
	v_mfma_f32_16x16x32_bf16 v[142:145], v[78:81], v[198:201], v[142:145]
	v_mfma_f32_16x16x32_bf16 v[138:141], v[122:125], v[198:201], v[138:141]
	v_mfma_f32_16x16x32_bf16 v[134:137], v[78:81], v[206:209], v[134:137]
	v_mfma_f32_16x16x32_bf16 v[130:133], v[122:125], v[206:209], v[130:133]
	v_mfma_f32_16x16x32_bf16 v[118:121], v[78:81], v[230:233], v[118:121]
	v_mfma_f32_16x16x32_bf16 v[114:117], v[122:125], v[230:233], v[114:117]
	v_mfma_f32_16x16x32_bf16 v[66:69], v[126:129], v[82:85], v[66:69]
	v_mfma_f32_16x16x32_bf16 v[62:65], v[176:179], v[82:85], v[62:65]
	v_mfma_f32_16x16x32_bf16 v[54:57], v[126:129], v[194:197], v[54:57]
	v_mfma_f32_16x16x32_bf16 v[50:53], v[176:179], v[194:197], v[50:53]
	v_mfma_f32_16x16x32_bf16 v[46:49], v[126:129], v[202:205], v[46:49]
	v_mfma_f32_16x16x32_bf16 v[42:45], v[176:179], v[202:205], v[42:45]
	v_mfma_f32_16x16x32_bf16 v[38:41], v[126:129], v[210:213], v[38:41]
	v_mfma_f32_16x16x32_bf16 v[34:37], v[176:179], v[210:213], v[34:37]
	v_mfma_f32_16x16x32_bf16 v[66:69], v[154:157], v[190:193], v[66:69]
	v_mfma_f32_16x16x32_bf16 v[62:65], v[186:189], v[190:193], v[62:65]
	v_mfma_f32_16x16x32_bf16 v[54:57], v[154:157], v[198:201], v[54:57]
	v_mfma_f32_16x16x32_bf16 v[50:53], v[186:189], v[198:201], v[50:53]
	v_mfma_f32_16x16x32_bf16 v[46:49], v[154:157], v[206:209], v[46:49]
	v_mfma_f32_16x16x32_bf16 v[42:45], v[186:189], v[206:209], v[42:45]
	v_mfma_f32_16x16x32_bf16 v[38:41], v[154:157], v[230:233], v[38:41]
	v_mfma_f32_16x16x32_bf16 v[34:37], v[186:189], v[230:233], v[34:37]
	s_barrier
	ds_read_b128 v[190:193], v185 offset:49152
	s_add_i32 m0, s30, 0x17f80
	ds_read_b128 v[194:197], v185 offset:50176
	global_load_lds_dwordx4 v16, s[8:9] offset:128
	s_add_i32 m0, s30, 0x19f80
	ds_read_b128 v[198:201], v185 offset:51200
	global_load_lds_dwordx4 v158, s[8:9] offset:128
	s_add_i32 m0, s30, 0x1bf80
	ds_read_b128 v[202:205], v185 offset:52224
	global_load_lds_dwordx4 v16, s[48:49] offset:128
	s_add_i32 m0, s30, 0x1df80
	ds_read_b128 v[206:209], v185 offset:53248
	global_load_lds_dwordx4 v158, s[48:49] offset:128
	s_add_i32 m0, s38, 0xffffff80
	ds_read_b128 v[210:213], v185 offset:54272
	global_load_lds_dwordx4 v162, s[24:25] offset:128
	s_add_i32 m0, s39, 0xffffff80
	ds_read_b128 v[230:233], v185 offset:55296
	global_load_lds_dwordx4 v160, s[24:25] offset:128
	ds_read_b128 v[234:237], v185 offset:56320
	s_waitcnt vmcnt(8) lgkmcnt(0)
	s_barrier
	v_mfma_f32_16x16x32_bf16 v[82:85], v[74:77], v[190:193], v[110:113]
	v_mfma_f32_16x16x32_bf16 v[110:113], v[78:81], v[194:197], v[82:85]
	v_mfma_f32_16x16x32_bf16 v[82:85], v[86:89], v[190:193], v[106:109]
	v_mfma_f32_16x16x32_bf16 v[106:109], v[122:125], v[194:197], v[82:85]
	v_mfma_f32_16x16x32_bf16 v[82:85], v[74:77], v[198:201], v[102:105]
	v_mfma_f32_16x16x32_bf16 v[102:105], v[78:81], v[202:205], v[82:85]
	v_mfma_f32_16x16x32_bf16 v[82:85], v[86:89], v[198:201], v[98:101]
	v_mfma_f32_16x16x32_bf16 v[98:101], v[122:125], v[202:205], v[82:85]
	v_mfma_f32_16x16x32_bf16 v[82:85], v[74:77], v[206:209], v[94:97]
	v_mfma_f32_16x16x32_bf16 v[94:97], v[78:81], v[210:213], v[82:85]
	v_mfma_f32_16x16x32_bf16 v[82:85], v[86:89], v[206:209], v[90:93]
	v_mfma_f32_16x16x32_bf16 v[58:61], v[74:77], v[230:233], v[58:61]
	v_mfma_f32_16x16x32_bf16 v[90:93], v[122:125], v[210:213], v[82:85]
	v_mfma_f32_16x16x32_bf16 v[82:85], v[78:81], v[234:237], v[58:61]
	v_mfma_f32_16x16x32_bf16 v[58:61], v[86:89], v[230:233], v[70:73]
	v_mfma_f32_16x16x32_bf16 v[78:81], v[122:125], v[234:237], v[58:61]
	v_mfma_f32_16x16x32_bf16 v[30:33], v[126:129], v[190:193], v[30:33]
	v_mfma_f32_16x16x32_bf16 v[26:29], v[176:179], v[190:193], v[26:29]
	v_mfma_f32_16x16x32_bf16 v[22:25], v[126:129], v[198:201], v[22:25]
	v_mfma_f32_16x16x32_bf16 v[18:21], v[176:179], v[198:201], v[18:21]
	v_mfma_f32_16x16x32_bf16 v[12:15], v[126:129], v[206:209], v[12:15]
	v_mfma_f32_16x16x32_bf16 v[8:11], v[176:179], v[206:209], v[8:11]
	v_mfma_f32_16x16x32_bf16 v[4:7], v[126:129], v[230:233], v[4:7]
	v_mfma_f32_16x16x32_bf16 v[0:3], v[176:179], v[230:233], v[0:3]
	v_mfma_f32_16x16x32_bf16 v[30:33], v[154:157], v[194:197], v[30:33]
	v_mfma_f32_16x16x32_bf16 v[26:29], v[186:189], v[194:197], v[26:29]
	v_mfma_f32_16x16x32_bf16 v[22:25], v[154:157], v[202:205], v[22:25]
	v_mfma_f32_16x16x32_bf16 v[18:21], v[186:189], v[202:205], v[18:21]
	v_mfma_f32_16x16x32_bf16 v[12:15], v[154:157], v[210:213], v[12:15]
	v_mfma_f32_16x16x32_bf16 v[8:11], v[186:189], v[210:213], v[8:11]
	v_mfma_f32_16x16x32_bf16 v[4:7], v[154:157], v[234:237], v[4:7]
	v_mfma_f32_16x16x32_bf16 v[0:3], v[186:189], v[234:237], v[0:3]
	s_barrier
	s_add_i32 s46, s46, 2
	s_add_u32 s6, s6, 0x100
	s_addc_u32 s7, s7, 0
	s_add_u32 s44, s44, 0x100
	s_addc_u32 s45, s45, 0
	s_cmp_gt_u32 s46, 5
	s_cbranch_scc0 .LBB0_552
	s_and_b64 vcc, exec, s[14:15]
	s_cbranch_vccz .LBB0_555
	s_barrier

.LBB0_1017:
	s_ashr_i32 s19, s18, 31
	s_lshl_b64 s[20:21], s[18:19], 20
	s_add_u32 s20, s34, s20
	s_addc_u32 s21, s35, s21
	s_and_b64 s[22:23], s[4:5], exec
	s_cselect_b32 s19, s21, s25
	s_cselect_b32 s31, s20, s24
	s_ashr_i32 s17, s16, 31
	s_lshl_b64 s[22:23], s[16:17], 20
	s_add_u32 s22, s36, s22
	s_addc_u32 s23, s37, s23
	s_and_b64 s[28:29], s[4:5], exec
	s_cselect_b32 s17, s23, s27
	s_cselect_b32 s55, s22, s26
	s_add_u32 s24, s24, 0x80080
	s_addc_u32 s25, s25, 0
	s_add_u32 s60, s26, 0x100
	v_mov_b32_e32 v50, 0
	s_addc_u32 s61, s27, 0
	s_mov_b32 s62, -2
	v_mov_b32_e32 v51, v50
	v_mov_b32_e32 v52, v50
	v_mov_b32_e32 v53, v50
	v_mov_b32_e32 v70, v50
	v_mov_b32_e32 v71, v50
	v_mov_b32_e32 v72, v50
	v_mov_b32_e32 v73, v50
	v_mov_b32_e32 v74, v50
	v_mov_b32_e32 v75, v50
	v_mov_b32_e32 v76, v50
	v_mov_b32_e32 v77, v50
	v_mov_b32_e32 v78, v50
	v_mov_b32_e32 v79, v50
	v_mov_b32_e32 v80, v50
	v_mov_b32_e32 v81, v50
	v_mov_b32_e32 v82, v50
	v_mov_b32_e32 v83, v50
	v_mov_b32_e32 v84, v50
	v_mov_b32_e32 v85, v50
	v_mov_b32_e32 v86, v50
	v_mov_b32_e32 v87, v50
	v_mov_b32_e32 v88, v50
	v_mov_b32_e32 v89, v50
	v_mov_b32_e32 v90, v50
	v_mov_b32_e32 v91, v50
	v_mov_b32_e32 v92, v50
	v_mov_b32_e32 v93, v50
	v_mov_b32_e32 v94, v50
	v_mov_b32_e32 v95, v50
	v_mov_b32_e32 v96, v50
	v_mov_b32_e32 v97, v50
	v_mov_b32_e32 v0, v50
	v_mov_b32_e32 v1, v50
	v_mov_b32_e32 v2, v50
	v_mov_b32_e32 v3, v50
	v_mov_b32_e32 v4, v50
	v_mov_b32_e32 v5, v50
	v_mov_b32_e32 v6, v50
	v_mov_b32_e32 v7, v50
	v_mov_b32_e32 v8, v50
	v_mov_b32_e32 v9, v50
	v_mov_b32_e32 v10, v50
	v_mov_b32_e32 v11, v50
	v_mov_b32_e32 v12, v50
	v_mov_b32_e32 v13, v50
	v_mov_b32_e32 v14, v50
	v_mov_b32_e32 v15, v50
	v_mov_b32_e32 v18, v50
	v_mov_b32_e32 v19, v50
	v_mov_b32_e32 v20, v50
	v_mov_b32_e32 v21, v50
	v_mov_b32_e32 v22, v50
	v_mov_b32_e32 v23, v50
	v_mov_b32_e32 v24, v50
	v_mov_b32_e32 v25, v50
	v_mov_b32_e32 v26, v50
	v_mov_b32_e32 v27, v50
	v_mov_b32_e32 v28, v50
	v_mov_b32_e32 v29, v50
	v_mov_b32_e32 v30, v50
	v_mov_b32_e32 v31, v50
	v_mov_b32_e32 v32, v50
	v_mov_b32_e32 v33, v50
	v_mov_b32_e32 v98, v50
	v_mov_b32_e32 v99, v50
	v_mov_b32_e32 v100, v50
	v_mov_b32_e32 v101, v50
	v_mov_b32_e32 v102, v50
	v_mov_b32_e32 v103, v50
	v_mov_b32_e32 v104, v50
	v_mov_b32_e32 v105, v50
	v_mov_b32_e32 v106, v50
	v_mov_b32_e32 v107, v50
	v_mov_b32_e32 v108, v50
	v_mov_b32_e32 v109, v50
	v_mov_b32_e32 v110, v50
	v_mov_b32_e32 v111, v50
	v_mov_b32_e32 v112, v50
	v_mov_b32_e32 v113, v50
	v_mov_b32_e32 v114, v50
	v_mov_b32_e32 v115, v50
	v_mov_b32_e32 v116, v50
	v_mov_b32_e32 v117, v50
	v_mov_b32_e32 v118, v50
	v_mov_b32_e32 v119, v50
	v_mov_b32_e32 v120, v50
	v_mov_b32_e32 v121, v50
	v_mov_b32_e32 v122, v50
	v_mov_b32_e32 v123, v50
	v_mov_b32_e32 v124, v50
	v_mov_b32_e32 v125, v50
	v_mov_b32_e32 v126, v50
	v_mov_b32_e32 v127, v50
	v_mov_b32_e32 v128, v50
	v_mov_b32_e32 v129, v50
	v_mov_b32_e32 v34, v50
	v_mov_b32_e32 v35, v50
	v_mov_b32_e32 v36, v50
	v_mov_b32_e32 v37, v50
	v_mov_b32_e32 v38, v50
	v_mov_b32_e32 v39, v50
	v_mov_b32_e32 v40, v50
	v_mov_b32_e32 v41, v50
	v_mov_b32_e32 v42, v50
	v_mov_b32_e32 v43, v50
	v_mov_b32_e32 v44, v50
	v_mov_b32_e32 v45, v50
	v_mov_b32_e32 v46, v50
	v_mov_b32_e32 v47, v50
	v_mov_b32_e32 v48, v50
	v_mov_b32_e32 v49, v50
	v_mov_b32_e32 v54, v50
	v_mov_b32_e32 v55, v50
	v_mov_b32_e32 v56, v50
	v_mov_b32_e32 v57, v50
	v_mov_b32_e32 v58, v50
	v_mov_b32_e32 v59, v50
	v_mov_b32_e32 v60, v50
	v_mov_b32_e32 v61, v50
	v_mov_b32_e32 v62, v50
	v_mov_b32_e32 v63, v50
	v_mov_b32_e32 v64, v50
	v_mov_b32_e32 v65, v50
	v_mov_b32_e32 v66, v50
	v_mov_b32_e32 v67, v50
	v_mov_b32_e32 v68, v50
	v_mov_b32_e32 v69, v50
	v_add_u32_e32 v168, 0x10000, v166
	v_add_u32_e32 v169, 0x14000, v166
	v_add_u32_e32 v170, 0x18000, v166
	v_add_u32_e32 v171, 0x1c000, v166
.LBB0_1018:
	s_add_u32 s26, s24, 0xfff80080
	s_addc_u32 s27, s25, -1
	s_cmp_eq_u32 s62, 28
	s_cselect_b32 s29, s19, s27
	s_cselect_b32 s28, s31, s26
	s_cselect_b32 s27, s17, s61
	s_cselect_b32 s26, s55, s60
	ds_read_b128 v[144:147], v168
	ds_read_b128 v[148:151], v168 offset:1024
	ds_read_b128 v[152:155], v168 offset:2048
	ds_read_b128 v[156:159], v168 offset:3072
	ds_read_b128 v[160:163], v169
	ds_read_b128 v[176:179], v169 offset:1024
	ds_read_b128 v[180:183], v169 offset:2048
	ds_read_b128 v[184:187], v169 offset:3072
	ds_read_b128 v[188:191], v167
	ds_read_b128 v[192:195], v167 offset:1024
	ds_read_b128 v[196:199], v167 offset:2048
	ds_read_b128 v[200:203], v167 offset:3072
	ds_read_b128 v[204:207], v167 offset:4096
	s_add_i32 m0, s39, 0xc000
	ds_read_b128 v[208:211], v167 offset:5120
	global_load_lds_dwordx4 v140, s[24:25]
	s_add_i32 m0, s39, 0xe000
	ds_read_b128 v[212:215], v167 offset:6144
	global_load_lds_dwordx4 v142, s[24:25]
	ds_read_b128 v[230:233], v167 offset:7168
	s_waitcnt vmcnt(8) lgkmcnt(0)
	s_barrier
	v_mfma_f32_16x16x32_bf16 v[66:69], v[144:147], v[188:191], v[66:69]
	v_mfma_f32_16x16x32_bf16 v[62:65], v[152:155], v[188:191], v[62:65]
	v_mfma_f32_16x16x32_bf16 v[58:61], v[144:147], v[196:199], v[58:61]
	v_mfma_f32_16x16x32_bf16 v[54:57], v[152:155], v[196:199], v[54:57]
	v_mfma_f32_16x16x32_bf16 v[46:49], v[144:147], v[204:207], v[46:49]
	v_mfma_f32_16x16x32_bf16 v[42:45], v[152:155], v[204:207], v[42:45]
	v_mfma_f32_16x16x32_bf16 v[38:41], v[144:147], v[212:215], v[38:41]
	v_mfma_f32_16x16x32_bf16 v[34:37], v[152:155], v[212:215], v[34:37]
	v_mfma_f32_16x16x32_bf16 v[66:69], v[148:151], v[192:195], v[66:69]
	v_mfma_f32_16x16x32_bf16 v[62:65], v[156:159], v[192:195], v[62:65]
	v_mfma_f32_16x16x32_bf16 v[58:61], v[148:151], v[200:203], v[58:61]
	v_mfma_f32_16x16x32_bf16 v[54:57], v[156:159], v[200:203], v[54:57]
	v_mfma_f32_16x16x32_bf16 v[46:49], v[148:151], v[208:211], v[46:49]
	v_mfma_f32_16x16x32_bf16 v[42:45], v[156:159], v[208:211], v[42:45]
	v_mfma_f32_16x16x32_bf16 v[38:41], v[148:151], v[230:233], v[38:41]
	v_mfma_f32_16x16x32_bf16 v[34:37], v[156:159], v[230:233], v[34:37]
	v_mfma_f32_16x16x32_bf16 v[126:129], v[160:163], v[188:191], v[126:129]
	v_mfma_f32_16x16x32_bf16 v[122:125], v[180:183], v[188:191], v[122:125]
	v_mfma_f32_16x16x32_bf16 v[118:121], v[160:163], v[196:199], v[118:121]
	v_mfma_f32_16x16x32_bf16 v[114:117], v[180:183], v[196:199], v[114:117]
	v_mfma_f32_16x16x32_bf16 v[110:113], v[160:163], v[204:207], v[110:113]
	v_mfma_f32_16x16x32_bf16 v[106:109], v[180:183], v[204:207], v[106:109]
	v_mfma_f32_16x16x32_bf16 v[102:105], v[160:163], v[212:215], v[102:105]
	v_mfma_f32_16x16x32_bf16 v[98:101], v[180:183], v[212:215], v[98:101]
	v_mfma_f32_16x16x32_bf16 v[126:129], v[176:179], v[192:195], v[126:129]
	v_mfma_f32_16x16x32_bf16 v[122:125], v[184:187], v[192:195], v[122:125]
	v_mfma_f32_16x16x32_bf16 v[118:121], v[176:179], v[200:203], v[118:121]
	v_mfma_f32_16x16x32_bf16 v[114:117], v[184:187], v[200:203], v[114:117]
	v_mfma_f32_16x16x32_bf16 v[110:113], v[176:179], v[208:211], v[110:113]
	v_mfma_f32_16x16x32_bf16 v[106:109], v[184:187], v[208:211], v[106:109]
	v_mfma_f32_16x16x32_bf16 v[102:105], v[176:179], v[230:233], v[102:105]
	v_mfma_f32_16x16x32_bf16 v[98:101], v[184:187], v[230:233], v[98:101]
	s_barrier
	ds_read_b128 v[188:191], v167 offset:16384
	s_add_i32 m0, s38, 0x10000
	ds_read_b128 v[192:195], v167 offset:17408
	global_load_lds_dwordx4 v132, s[26:27]
	s_add_i32 m0, s38, 0x12000
	s_add_u32 s64, s26, 0x80000
	s_addc_u32 s65, s27, 0
	ds_read_b128 v[196:199], v167 offset:18432
	global_load_lds_dwordx4 v136, s[26:27]
	s_add_i32 m0, s38, 0x14000
	ds_read_b128 v[200:203], v167 offset:19456
	global_load_lds_dwordx4 v132, s[64:65]
	s_add_i32 m0, s38, 0x16000
	ds_read_b128 v[204:207], v167 offset:20480
	global_load_lds_dwordx4 v136, s[64:65]
	s_mov_b32 m0, s39
	ds_read_b128 v[208:211], v167 offset:21504
	global_load_lds_dwordx4 v130, s[28:29]
	s_mov_b32 m0, s40
	ds_read_b128 v[212:215], v167 offset:22528
	global_load_lds_dwordx4 v134, s[28:29]
	ds_read_b128 v[230:233], v167 offset:23552
	s_waitcnt vmcnt(8) lgkmcnt(0)
	s_barrier
	v_mfma_f32_16x16x32_bf16 v[30:33], v[144:147], v[188:191], v[30:33]
	v_mfma_f32_16x16x32_bf16 v[26:29], v[152:155], v[188:191], v[26:29]
	v_mfma_f32_16x16x32_bf16 v[22:25], v[144:147], v[196:199], v[22:25]
	v_mfma_f32_16x16x32_bf16 v[18:21], v[152:155], v[196:199], v[18:21]
	v_mfma_f32_16x16x32_bf16 v[12:15], v[144:147], v[204:207], v[12:15]
	v_mfma_f32_16x16x32_bf16 v[8:11], v[152:155], v[204:207], v[8:11]
	v_mfma_f32_16x16x32_bf16 v[4:7], v[144:147], v[212:215], v[4:7]
	v_mfma_f32_16x16x32_bf16 v[0:3], v[152:155], v[212:215], v[0:3]
	v_mfma_f32_16x16x32_bf16 v[30:33], v[148:151], v[192:195], v[30:33]
	v_mfma_f32_16x16x32_bf16 v[26:29], v[156:159], v[192:195], v[26:29]
	v_mfma_f32_16x16x32_bf16 v[22:25], v[148:151], v[200:203], v[22:25]
	v_mfma_f32_16x16x32_bf16 v[18:21], v[156:159], v[200:203], v[18:21]
	v_mfma_f32_16x16x32_bf16 v[12:15], v[148:151], v[208:211], v[12:15]
	v_mfma_f32_16x16x32_bf16 v[8:11], v[156:159], v[208:211], v[8:11]
	v_mfma_f32_16x16x32_bf16 v[4:7], v[148:151], v[230:233], v[4:7]
	v_mfma_f32_16x16x32_bf16 v[0:3], v[156:159], v[230:233], v[0:3]
	v_mfma_f32_16x16x32_bf16 v[94:97], v[160:163], v[188:191], v[94:97]
	v_mfma_f32_16x16x32_bf16 v[90:93], v[180:183], v[188:191], v[90:93]
	v_mfma_f32_16x16x32_bf16 v[86:89], v[160:163], v[196:199], v[86:89]
	v_mfma_f32_16x16x32_bf16 v[82:85], v[180:183], v[196:199], v[82:85]
	v_mfma_f32_16x16x32_bf16 v[78:81], v[160:163], v[204:207], v[78:81]
	v_mfma_f32_16x16x32_bf16 v[74:77], v[180:183], v[204:207], v[74:77]
	v_mfma_f32_16x16x32_bf16 v[70:73], v[160:163], v[212:215], v[70:73]
	v_mfma_f32_16x16x32_bf16 v[50:53], v[180:183], v[212:215], v[50:53]
	v_mfma_f32_16x16x32_bf16 v[94:97], v[176:179], v[192:195], v[94:97]
	v_mfma_f32_16x16x32_bf16 v[90:93], v[184:187], v[192:195], v[90:93]
	v_mfma_f32_16x16x32_bf16 v[86:89], v[176:179], v[200:203], v[86:89]
	v_mfma_f32_16x16x32_bf16 v[82:85], v[184:187], v[200:203], v[82:85]
	v_mfma_f32_16x16x32_bf16 v[78:81], v[176:179], v[208:211], v[78:81]
	v_mfma_f32_16x16x32_bf16 v[74:77], v[184:187], v[208:211], v[74:77]
	v_mfma_f32_16x16x32_bf16 v[70:73], v[176:179], v[230:233], v[70:73]
	v_mfma_f32_16x16x32_bf16 v[50:53], v[184:187], v[230:233], v[50:53]
	s_barrier
	s_add_u32 s100, s28, 0x80000
	s_addc_u32 s101, s29, 0
	ds_read_b128 v[144:147], v170
	ds_read_b128 v[148:151], v170 offset:1024
	ds_read_b128 v[152:155], v170 offset:2048
	ds_read_b128 v[156:159], v170 offset:3072
	ds_read_b128 v[160:163], v171
	ds_read_b128 v[176:179], v171 offset:1024
	ds_read_b128 v[180:183], v171 offset:2048
	ds_read_b128 v[184:187], v171 offset:3072
	ds_read_b128 v[188:191], v167 offset:32768
	ds_read_b128 v[192:195], v167 offset:33792
	ds_read_b128 v[196:199], v167 offset:34816
	ds_read_b128 v[200:203], v167 offset:35840
	ds_read_b128 v[204:207], v167 offset:36864
	s_mov_b32 m0, s41
	ds_read_b128 v[208:211], v167 offset:37888
	global_load_lds_dwordx4 v130, s[100:101]
	s_mov_b32 m0, s42
	ds_read_b128 v[212:215], v167 offset:38912
	global_load_lds_dwordx4 v134, s[100:101]
	ds_read_b128 v[230:233], v167 offset:39936
	s_waitcnt vmcnt(8) lgkmcnt(0)
	s_barrier
	v_mfma_f32_16x16x32_bf16 v[66:69], v[144:147], v[188:191], v[66:69]
	v_mfma_f32_16x16x32_bf16 v[62:65], v[152:155], v[188:191], v[62:65]
	v_mfma_f32_16x16x32_bf16 v[58:61], v[144:147], v[196:199], v[58:61]
	v_mfma_f32_16x16x32_bf16 v[54:57], v[152:155], v[196:199], v[54:57]
	v_mfma_f32_16x16x32_bf16 v[46:49], v[144:147], v[204:207], v[46:49]
	v_mfma_f32_16x16x32_bf16 v[42:45], v[152:155], v[204:207], v[42:45]
	v_mfma_f32_16x16x32_bf16 v[38:41], v[144:147], v[212:215], v[38:41]
	v_mfma_f32_16x16x32_bf16 v[34:37], v[152:155], v[212:215], v[34:37]
	v_mfma_f32_16x16x32_bf16 v[66:69], v[148:151], v[192:195], v[66:69]
	v_mfma_f32_16x16x32_bf16 v[62:65], v[156:159], v[192:195], v[62:65]
	v_mfma_f32_16x16x32_bf16 v[58:61], v[148:151], v[200:203], v[58:61]
	v_mfma_f32_16x16x32_bf16 v[54:57], v[156:159], v[200:203], v[54:57]
	v_mfma_f32_16x16x32_bf16 v[46:49], v[148:151], v[208:211], v[46:49]
	v_mfma_f32_16x16x32_bf16 v[42:45], v[156:159], v[208:211], v[42:45]
	v_mfma_f32_16x16x32_bf16 v[38:41], v[148:151], v[230:233], v[38:41]
	v_mfma_f32_16x16x32_bf16 v[34:37], v[156:159], v[230:233], v[34:37]
	v_mfma_f32_16x16x32_bf16 v[126:129], v[160:163], v[188:191], v[126:129]
	v_mfma_f32_16x16x32_bf16 v[122:125], v[180:183], v[188:191], v[122:125]
	v_mfma_f32_16x16x32_bf16 v[118:121], v[160:163], v[196:199], v[118:121]
	v_mfma_f32_16x16x32_bf16 v[114:117], v[180:183], v[196:199], v[114:117]
	v_mfma_f32_16x16x32_bf16 v[110:113], v[160:163], v[204:207], v[110:113]
	v_mfma_f32_16x16x32_bf16 v[106:109], v[180:183], v[204:207], v[106:109]
	v_mfma_f32_16x16x32_bf16 v[102:105], v[160:163], v[212:215], v[102:105]
	v_mfma_f32_16x16x32_bf16 v[98:101], v[180:183], v[212:215], v[98:101]
	v_mfma_f32_16x16x32_bf16 v[126:129], v[176:179], v[192:195], v[126:129]
	v_mfma_f32_16x16x32_bf16 v[122:125], v[184:187], v[192:195], v[122:125]
	v_mfma_f32_16x16x32_bf16 v[118:121], v[176:179], v[200:203], v[118:121]
	v_mfma_f32_16x16x32_bf16 v[114:117], v[184:187], v[200:203], v[114:117]
	v_mfma_f32_16x16x32_bf16 v[110:113], v[176:179], v[208:211], v[110:113]
	v_mfma_f32_16x16x32_bf16 v[106:109], v[184:187], v[208:211], v[106:109]
	v_mfma_f32_16x16x32_bf16 v[102:105], v[176:179], v[230:233], v[102:105]
	v_mfma_f32_16x16x32_bf16 v[98:101], v[184:187], v[230:233], v[98:101]
	s_barrier
	ds_read_b128 v[188:191], v167 offset:49152
	s_add_i32 m0, s38, 0x17f80
	ds_read_b128 v[192:195], v167 offset:50176
	global_load_lds_dwordx4 v132, s[26:27] offset:128
	s_add_i32 m0, s38, 0x19f80
	ds_read_b128 v[196:199], v167 offset:51200
	global_load_lds_dwordx4 v136, s[26:27] offset:128
	s_add_i32 m0, s38, 0x1bf80
	ds_read_b128 v[200:203], v167 offset:52224
	global_load_lds_dwordx4 v132, s[64:65] offset:128
	s_add_i32 m0, s38, 0x1df80
	ds_read_b128 v[204:207], v167 offset:53248
	global_load_lds_dwordx4 v136, s[64:65] offset:128
	s_add_i32 m0, s46, 0xffffff80
	ds_read_b128 v[208:211], v167 offset:54272
	global_load_lds_dwordx4 v130, s[28:29] offset:128
	s_add_i32 m0, s47, 0xffffff80
	ds_read_b128 v[212:215], v167 offset:55296
	global_load_lds_dwordx4 v134, s[28:29] offset:128
	ds_read_b128 v[230:233], v167 offset:56320
	s_waitcnt vmcnt(8) lgkmcnt(0)
	s_barrier
	v_mfma_f32_16x16x32_bf16 v[30:33], v[144:147], v[188:191], v[30:33]
	v_mfma_f32_16x16x32_bf16 v[26:29], v[152:155], v[188:191], v[26:29]
	v_mfma_f32_16x16x32_bf16 v[22:25], v[144:147], v[196:199], v[22:25]
	v_mfma_f32_16x16x32_bf16 v[18:21], v[152:155], v[196:199], v[18:21]
	v_mfma_f32_16x16x32_bf16 v[12:15], v[144:147], v[204:207], v[12:15]
	v_mfma_f32_16x16x32_bf16 v[8:11], v[152:155], v[204:207], v[8:11]
	v_mfma_f32_16x16x32_bf16 v[4:7], v[144:147], v[212:215], v[4:7]
	v_mfma_f32_16x16x32_bf16 v[0:3], v[152:155], v[212:215], v[0:3]
	v_mfma_f32_16x16x32_bf16 v[30:33], v[148:151], v[192:195], v[30:33]
	v_mfma_f32_16x16x32_bf16 v[26:29], v[156:159], v[192:195], v[26:29]
	v_mfma_f32_16x16x32_bf16 v[22:25], v[148:151], v[200:203], v[22:25]
	v_mfma_f32_16x16x32_bf16 v[18:21], v[156:159], v[200:203], v[18:21]
	v_mfma_f32_16x16x32_bf16 v[12:15], v[148:151], v[208:211], v[12:15]
	v_mfma_f32_16x16x32_bf16 v[8:11], v[156:159], v[208:211], v[8:11]
	v_mfma_f32_16x16x32_bf16 v[4:7], v[148:151], v[230:233], v[4:7]
	v_mfma_f32_16x16x32_bf16 v[0:3], v[156:159], v[230:233], v[0:3]
	v_mfma_f32_16x16x32_bf16 v[94:97], v[160:163], v[188:191], v[94:97]
	v_mfma_f32_16x16x32_bf16 v[90:93], v[180:183], v[188:191], v[90:93]
	v_mfma_f32_16x16x32_bf16 v[86:89], v[160:163], v[196:199], v[86:89]
	v_mfma_f32_16x16x32_bf16 v[82:85], v[180:183], v[196:199], v[82:85]
	v_mfma_f32_16x16x32_bf16 v[78:81], v[160:163], v[204:207], v[78:81]
	v_mfma_f32_16x16x32_bf16 v[74:77], v[180:183], v[204:207], v[74:77]
	v_mfma_f32_16x16x32_bf16 v[70:73], v[160:163], v[212:215], v[70:73]
	v_mfma_f32_16x16x32_bf16 v[50:53], v[180:183], v[212:215], v[50:53]
	v_mfma_f32_16x16x32_bf16 v[94:97], v[176:179], v[192:195], v[94:97]
	v_mfma_f32_16x16x32_bf16 v[90:93], v[184:187], v[192:195], v[90:93]
	v_mfma_f32_16x16x32_bf16 v[86:89], v[176:179], v[200:203], v[86:89]
	v_mfma_f32_16x16x32_bf16 v[82:85], v[184:187], v[200:203], v[82:85]
	v_mfma_f32_16x16x32_bf16 v[78:81], v[176:179], v[208:211], v[78:81]
	v_mfma_f32_16x16x32_bf16 v[74:77], v[184:187], v[208:211], v[74:77]
	v_mfma_f32_16x16x32_bf16 v[70:73], v[176:179], v[230:233], v[70:73]
	v_mfma_f32_16x16x32_bf16 v[50:53], v[184:187], v[230:233], v[50:53]
	s_barrier
	s_add_i32 s62, s62, 2
	s_add_u32 s24, s24, 0x100
	s_addc_u32 s25, s25, 0
	s_add_u32 s60, s60, 0x100
	s_addc_u32 s61, s61, 0
	s_cmp_gt_u32 s62, 29
	s_cbranch_scc0 .LBB0_1018
	s_and_b64 vcc, exec, s[8:9]
	s_cbranch_vccz .LBB0_1021
	s_barrier
